# GEMM epilogue loads (gate tiles in up-projection, residual rows in W_out and MLP-down) fetched in a 4-rows-x-64-B-per-quarter pattern and permuted back through LDS; plus vres block, rstd pipelining, P
# speedup vs baseline: 1.0083x; 1.0083x over previous
;     DI bool next(int i, Unit& u) const { const long L = (long)i * G + c; if (L >= T.nwg) return false; T.map((int)L, u.pm, u.pn); u.seg = 0; return true; }
;     DI bool next(int i, Unit& u) const { const int ti = i / 3; const long L = (long)ti * G + c; if (L >= T.nwg) return false; T.map((int)L, u.pm, u.pn); u.seg = i - 3 * ti; return true; }
;     DI const char* aptr(const Unit& u) const { return A + (size_t)u.pm * ta + (size_t)kofs(u.seg) * 2; }
;     DI const char* bptr(const Unit& u) const { return B + (size_t)u.pn * tb + (size_t)kofs(u.seg) * 2; }
; #define PG8_STAGE(bufoff, gbase, voff) do { _Pragma("unroll") for (int _i = 0; _i < 2; ++_i) \
;         __builtin_amdgcn_global_load_lds((const unsigned*)((const char*)(gbase) + (voff)[_i]), (LAS unsigned*)(lds + (bufoff) + ldsw + _i * 8192), 16, 0, 0); } while (0)
; #define PG8_WAIT_V(n) asm volatile("s_waitcnt vmcnt(" #n ")" ::: "memory")
; #define PG8_BAR __builtin_amdgcn_s_barrier()
; template <class Epi, class Sched>
; DI void gemm_phase(LAS unsigned char* lds, const int wv, const int lda, const int ldb, const Sched& S, const Epi& E) {
;     ...
;     Unit cur, nxt; int ui = 0;
;     if (!S.next(0, cur)) return;
;     f32x4 acc[2][2][4][2];
; #pragma unroll
;     for (int a = 0; a < 2; ++a)
; #pragma unroll
;         for (int b = 0; b < 2; ++b)
; #pragma unroll
;             for (int m = 0; m < 4; ++m)
; #pragma unroll
;                 for (int n = 0; n < 2; ++n) acc[a][b][m][n] = (f32x4){0.f, 0.f, 0.f, 0.f};
;     bf16x8 At[4][2], B0[2][2], B1[2][2];
;     const char* cA = S.aptr(cur); const char* cB = S.bptr(cur); int nt = S.ntiles(cur);
;     PG8_STAGE(PG8_SB(0, 0), cB, voffB); PG8_STAGE(PG8_SB(0, 1), cB + hstepB, voffB); PG8_STAGE(PG8_SA(0, 0), cA, voffA); PG8_STAGE(PG8_SA(0, 1), cA + hstepA, voffA);
;     if (wr == 1) PG8_BAR;
;     PG8_WAIT_V(2); PG8_BAR;
;     PG8_STAGE(PG8_SB(1, 0), cB + kstep, voffB); PG8_STAGE(PG8_SA(1, 0), cA + kstep, voffA); PG8_STAGE(PG8_SB(1, 1), cB + hstepB + kstep, voffB);
;     PG8_WAIT_V(6); PG8_BAR;
.LBB0_1171:
	s_add_u32 s8, s4, 0x23c28000
	v_lshrrev_b32_e32 v16, 1, v8
	s_addc_u32 s9, s5, 0
	v_and_b32_e32 v16, 24, v16
	s_add_u32 s10, s4, 0x1fc28000
	v_and_b32_e32 v15, 15, v8
	v_lshlrev_b32_e32 v17, 1, v16
	v_lshlrev_b32_e32 v8, 2, v8
	s_addc_u32 s11, s5, 0
	v_lshl_or_b32 v186, s0, 6, v15
	v_lshl_or_b32 v15, v15, 6, v17
	s_lshl_b32 s0, s0, 13
	v_and_b32_e32 v8, 32, v8
	v_bitop3_b32 v17, v15, s0, v8 bitop3:0xde
	s_lshl_b32 s0, s1, 5
	s_and_b32 s4, s0, 0x60
	s_add_i32 m0, s45, 0x18000
	v_lshl_add_u64 v[6:7], v[6:7], 0, s[28:29]
	s_lshl_b32 s0, s4, 7
	s_waitcnt vmcnt(2)
	s_barrier
	global_load_lds_dwordx4 v[6:7], off
	v_lshl_add_u64 v[4:5], v[4:5], 0, s[28:29]
	s_add_i32 m0, s45, 0x1a000
	s_add_i32 s49, s45, 0x8000
	s_add_i32 s50, s45, 0xa000
	v_bitop3_b32 v233, v15, s0, v8 bitop3:0xde
	global_load_lds_dwordx4 v[4:5], off
	v_lshl_add_u64 v[0:1], v[0:1], 0, s[28:29]
	s_mov_b32 m0, s49
	s_add_u32 s0, s34, 0x80080
	global_load_lds_dwordx4 v[0:1], off
	v_lshl_add_u64 v[0:1], v[2:3], 0, s[28:29]
	s_mov_b32 m0, s50
	s_addc_u32 s1, s35, 0
	global_load_lds_dwordx4 v[0:1], off
	s_add_i32 m0, s45, 0x1c000
	v_lshl_add_u64 v[0:1], s[0:1], 0, v[184:185]
	global_load_lds_dwordx4 v[0:1], off
	v_lshl_add_u64 v[0:1], s[0:1], 0, v[204:205]
	s_add_i32 m0, s45, 0x1e000
	s_cmpk_lt_u32 s6, 0x100
	global_load_lds_dwordx4 v[0:1], off
	v_lshlrev_b32_e32 v0, 15, v9
	v_and_b32_e32 v0, 0xffff0000, v0
	v_lshl_add_u32 v0, v10, 12, v0
	v_and_b32_e32 v1, 1, v9
	v_lshl_or_b32 v0, v1, 6, v0
	v_lshl_add_u32 v206, v11, 1, v0
	v_lshlrev_b32_e32 v0, 15, v12
	v_and_b32_e32 v0, 0xffff0000, v0
	v_lshl_add_u32 v0, v13, 12, v0
	v_and_b32_e32 v1, 1, v12
	s_waitcnt vmcnt(6)
	v_lshl_or_b32 v0, v1, 6, v0
	v_lshl_add_u32 v208, v14, 1, v0
	v_mov_b32_e32 v0, 0
	s_cselect_b64 s[12:13], -1, 0
	s_ashr_i32 s51, s17, 31
	v_or_b32_e32 v234, s4, v16
	s_mov_b32 s27, 12
	v_mov_b32_e32 v207, v185
	v_mov_b32_e32 v209, v185
	s_mov_b32 s33, 0
	v_add_u32_e32 v235, 0, v17
	s_mov_b32 s52, 0
	v_mov_b32_e32 v1, v0
	v_mov_b32_e32 v2, v0
	v_mov_b32_e32 v3, v0
	v_mov_b32_e32 v4, v0
	v_mov_b32_e32 v5, v0
	v_mov_b32_e32 v6, v0
	v_mov_b32_e32 v7, v0
	v_mov_b32_e32 v8, v0
	v_mov_b32_e32 v9, v0
	v_mov_b32_e32 v10, v0
	v_mov_b32_e32 v11, v0
	v_mov_b32_e32 v12, v0
	v_mov_b32_e32 v13, v0
	v_mov_b32_e32 v14, v0
	v_mov_b32_e32 v15, v0
	v_mov_b32_e32 v16, v0
	v_mov_b32_e32 v17, v0
	v_mov_b32_e32 v18, v0
	v_mov_b32_e32 v19, v0
	v_mov_b32_e32 v20, v0
	v_mov_b32_e32 v21, v0
	v_mov_b32_e32 v22, v0
	v_mov_b32_e32 v23, v0
	v_mov_b32_e32 v24, v0
	v_mov_b32_e32 v25, v0
	v_mov_b32_e32 v26, v0
	v_mov_b32_e32 v27, v0
	v_mov_b32_e32 v28, v0
	v_mov_b32_e32 v29, v0
	v_mov_b32_e32 v30, v0
	v_mov_b32_e32 v31, v0
	v_mov_b32_e32 v32, v0
	v_mov_b32_e32 v33, v0
	v_mov_b32_e32 v34, v0
	v_mov_b32_e32 v35, v0
	v_mov_b32_e32 v36, v0
	v_mov_b32_e32 v37, v0
	v_mov_b32_e32 v38, v0
	v_mov_b32_e32 v39, v0
	v_mov_b32_e32 v40, v0
	v_mov_b32_e32 v41, v0
	v_mov_b32_e32 v42, v0
	v_mov_b32_e32 v43, v0
	v_mov_b32_e32 v44, v0
	v_mov_b32_e32 v45, v0
	v_mov_b32_e32 v46, v0
	v_mov_b32_e32 v47, v0
	v_mov_b32_e32 v48, v0
	v_mov_b32_e32 v49, v0
	v_mov_b32_e32 v50, v0
	v_mov_b32_e32 v51, v0
	v_mov_b32_e32 v52, v0
	v_mov_b32_e32 v53, v0
	v_mov_b32_e32 v54, v0
	v_mov_b32_e32 v55, v0
	v_mov_b32_e32 v56, v0
	v_mov_b32_e32 v57, v0
	v_mov_b32_e32 v58, v0
	v_mov_b32_e32 v59, v0
	v_mov_b32_e32 v60, v0
	v_mov_b32_e32 v61, v0
	v_mov_b32_e32 v62, v0
	v_mov_b32_e32 v63, v0
	v_mov_b32_e32 v64, v0
	v_mov_b32_e32 v65, v0
	v_mov_b32_e32 v66, v0
	v_mov_b32_e32 v67, v0
	v_mov_b32_e32 v68, v0
	v_mov_b32_e32 v69, v0
	v_mov_b32_e32 v70, v0
	v_mov_b32_e32 v71, v0
	v_mov_b32_e32 v72, v0
	v_mov_b32_e32 v73, v0
	v_mov_b32_e32 v74, v0
	v_mov_b32_e32 v75, v0
	v_mov_b32_e32 v76, v0
	v_mov_b32_e32 v77, v0
	v_mov_b32_e32 v78, v0
	v_mov_b32_e32 v79, v0
	v_mov_b32_e32 v80, v0
	v_mov_b32_e32 v81, v0
	v_mov_b32_e32 v82, v0
	v_mov_b32_e32 v83, v0
	v_mov_b32_e32 v84, v0
	v_mov_b32_e32 v85, v0
	v_mov_b32_e32 v86, v0
	v_mov_b32_e32 v87, v0
	v_mov_b32_e32 v88, v0
	v_mov_b32_e32 v89, v0
	v_mov_b32_e32 v90, v0
	v_mov_b32_e32 v91, v0
	v_mov_b32_e32 v92, v0
	v_mov_b32_e32 v93, v0
	v_mov_b32_e32 v94, v0
	v_mov_b32_e32 v95, v0
	v_mov_b32_e32 v96, v0
	v_mov_b32_e32 v97, v0
	v_mov_b32_e32 v98, v0
	v_mov_b32_e32 v99, v0
	v_mov_b32_e32 v100, v0
	v_mov_b32_e32 v101, v0
	v_mov_b32_e32 v102, v0
	v_mov_b32_e32 v103, v0
	v_mov_b32_e32 v104, v0
	v_mov_b32_e32 v105, v0
	v_mov_b32_e32 v106, v0
	v_mov_b32_e32 v107, v0
	v_mov_b32_e32 v108, v0
	v_mov_b32_e32 v109, v0
	v_mov_b32_e32 v110, v0
	v_mov_b32_e32 v111, v0
	v_mov_b32_e32 v112, v0
	v_mov_b32_e32 v113, v0
	v_mov_b32_e32 v114, v0
	v_mov_b32_e32 v115, v0
	v_mov_b32_e32 v116, v0
	v_mov_b32_e32 v117, v0
	v_mov_b32_e32 v118, v0
	v_mov_b32_e32 v119, v0
	v_mov_b32_e32 v120, v0
	v_mov_b32_e32 v121, v0
	v_mov_b32_e32 v122, v0
	v_mov_b32_e32 v123, v0
	v_mov_b32_e32 v124, v0
	v_mov_b32_e32 v125, v0
	v_mov_b32_e32 v126, v0
	v_mov_b32_e32 v127, v0
	s_barrier
	v_mbcnt_lo_u32_b32 v248, -1, 0
	v_mbcnt_hi_u32_b32 v248, -1, v248
	s_lshl_b32 s98, s90, 10
	s_add_i32 s98, s98, 0x22000
	v_lshl_add_u32 v246, v248, 4, s98
	v_and_b32_e32 v249, 15, v248
	v_lshrrev_b32_e32 v242, 4, v248
	v_lshrrev_b32_e32 v243, 2, v249
	v_lshl_add_u32 v242, v243, 4, v242
	v_and_b32_e32 v243, 3, v249
	v_lshl_add_u32 v242, v243, 2, v242
	v_lshl_add_u32 v247, v242, 4, s98
	v_lshrrev_b32_e32 v242, 4, v248
	v_bfe_u32 v243, v248, 2, 2
	v_lshl_add_u32 v243, v242, 2, v243
	v_sub_u32_e32 v243, v243, v249
	v_and_b32_e32 v249, 3, v248
	v_sub_u32_e32 v249, v249, v242
	v_lshlrev_b32_e32 v249, 4, v249
	s_movk_i32 s98, 0x5a00
	v_mad_i32_i24 v240, v243, s98, v249
	v_ashrrev_i32_e32 v241, 31, v240
	s_branch .LBB0_1174

; #define GAS __attribute__((address_space(1)))
;     DI bool operator()(AccT& acc, const Unit& u, int wr, int wc, int fr, int fq) const {
;     ...
;         for (int ai = 0; ai < 2; ++ai) {
;             u32x4 ga[2][4], gb[2][4];
; #pragma unroll
;             for (int bj = 0; bj < 2; ++bj)
; #pragma unroll
;                 for (int m = 0; m < 4; ++m) { const bf16* zr = Z + (size_t)(row0 + ai * HALF + m * 16) * ZP + ZC_GATE + col0 + bj * HALF;
;                     ga[bj][m] = *(const GAS u32x4*)(zr + seg * D); gb[bj][m] = *(const GAS u32x4*)(zr + (seg < 2 ? seg + 1 : seg) * D); }
;             __builtin_amdgcn_sched_barrier(0);
.LBB0_1188:
	s_lshl_b32 s0, s33, 11
	s_ashr_i32 s1, s0, 31
	s_cmp_lt_i32 s33, 2
	s_cselect_b64 s[6:7], -1, 0
	s_cmp_lg_u64 s[6:7], 0
	s_addc_u32 s15, s33, 0
	v_lshl_add_u32 v212, s26, 8, v186
	s_lshl_b32 s26, s15, 11
	v_lshl_or_b32 v210, s30, 8, v234
	s_ashr_i32 s27, s26, 31
	v_ashrrev_i32_e32 v211, 31, v210
	s_cmp_eq_u32 s33, 2
	v_mov_b64_e32 v[128:129], s[8:9]
	s_movk_i32 s15, 0x5a00
	v_or_b32_e32 v222, 16, v212
	v_or_b32_e32 v220, 32, v212
	v_or_b32_e32 v216, 48, v212
	s_cselect_b64 s[34:35], -1, 0
	s_lshl_b64 s[30:31], s[0:1], 1
	v_mad_i64_i32 v[130:131], s[0:1], v212, s15, v[128:129]
	v_lshlrev_b64 v[214:215], 1, v[210:211]
	v_mad_i64_i32 v[134:135], s[0:1], v222, s15, v[128:129]
	v_mad_i64_i32 v[138:139], s[0:1], v220, s15, v[128:129]
	v_mad_i64_i32 v[128:129], s[0:1], v216, s15, v[128:129]
	v_lshl_add_u64 v[130:131], v[130:131], 0, v[214:215]
	s_mov_b64 s[36:37], 0x27e0
	v_lshl_add_u64 v[134:135], v[134:135], 0, v[214:215]
	v_lshl_add_u64 v[138:139], v[138:139], 0, v[214:215]
	v_lshl_add_u64 v[128:129], v[128:129], 0, v[214:215]
	s_lshl_b64 s[26:27], s[26:27], 1
	v_lshl_add_u64 v[130:131], v[130:131], 0, s[36:37]
	v_lshl_add_u64 v[134:135], v[134:135], 0, s[36:37]
	v_lshl_add_u64 v[138:139], v[138:139], 0, s[36:37]
	v_lshl_add_u64 v[128:129], v[128:129], 0, s[36:37]
	v_lshl_add_u64 v[132:133], v[130:131], 0, s[30:31]
	v_lshl_add_u64 v[130:131], v[130:131], 0, s[26:27]
	v_lshl_add_u64 v[136:137], v[134:135], 0, s[30:31]
	v_lshl_add_u64 v[134:135], v[134:135], 0, s[26:27]
	v_lshl_add_u64 v[140:141], v[138:139], 0, s[30:31]
	v_lshl_add_u64 v[138:139], v[138:139], 0, s[26:27]
	v_lshl_add_u64 v[160:161], v[128:129], 0, s[30:31]
	v_lshl_add_u64 v[128:129], v[128:129], 0, s[26:27]
	v_lshl_add_u64 v[242:243], v[132:133], 0, v[240:241]
	global_load_dwordx4 v[188:191], v[242:243], off
	v_lshl_add_u64 v[244:245], v[132:133], 0, v[240:241]
	global_load_dwordx4 v[156:159], v[244:245], off offset:256
	v_lshl_add_u64 v[242:243], v[130:131], 0, v[240:241]
	global_load_dwordx4 v[196:199], v[242:243], off
	v_lshl_add_u64 v[244:245], v[130:131], 0, v[240:241]
	global_load_dwordx4 v[152:155], v[244:245], off offset:256
	v_lshl_add_u64 v[242:243], v[136:137], 0, v[240:241]
	global_load_dwordx4 v[180:183], v[242:243], off
	v_lshl_add_u64 v[244:245], v[136:137], 0, v[240:241]
	global_load_dwordx4 v[148:151], v[244:245], off offset:256
	v_lshl_add_u64 v[242:243], v[134:135], 0, v[240:241]
	global_load_dwordx4 v[176:179], v[242:243], off
	v_lshl_add_u64 v[244:245], v[134:135], 0, v[240:241]
	global_load_dwordx4 v[144:147], v[244:245], off offset:256
	v_lshl_add_u64 v[242:243], v[140:141], 0, v[240:241]
	global_load_dwordx4 v[172:175], v[242:243], off
	s_nop 0
	v_lshl_add_u64 v[244:245], v[140:141], 0, v[240:241]
	global_load_dwordx4 v[140:143], v[244:245], off offset:256
	s_nop 0
	v_lshl_add_u64 v[242:243], v[138:139], 0, v[240:241]
	global_load_dwordx4 v[168:171], v[242:243], off
	s_nop 0
	v_lshl_add_u64 v[244:245], v[138:139], 0, v[240:241]
	global_load_dwordx4 v[136:139], v[244:245], off offset:256
	s_nop 0
	v_lshl_add_u64 v[242:243], v[160:161], 0, v[240:241]
	global_load_dwordx4 v[164:167], v[242:243], off
	v_lshl_add_u64 v[244:245], v[160:161], 0, v[240:241]
	global_load_dwordx4 v[132:135], v[244:245], off offset:256
	s_nop 0
	v_lshl_add_u64 v[242:243], v[128:129], 0, v[240:241]
	global_load_dwordx4 v[160:163], v[242:243], off
	s_nop 0
	v_lshl_add_u64 v[244:245], v[128:129], 0, v[240:241]
	global_load_dwordx4 v[128:131], v[244:245], off offset:256
	s_cmp_lg_u32 s33, 2
	v_ashrrev_i32_e32 v213, 31, v212
	s_waitcnt vmcnt(0)
	ds_write_b128 v246, v[188:191]
	ds_read_b128 v[188:191], v247
	ds_write_b128 v246, v[156:159]
	ds_read_b128 v[156:159], v247
	ds_write_b128 v246, v[196:199]
	ds_read_b128 v[196:199], v247
	ds_write_b128 v246, v[152:155]
	ds_read_b128 v[152:155], v247
	ds_write_b128 v246, v[180:183]
	ds_read_b128 v[180:183], v247
	ds_write_b128 v246, v[148:151]
	ds_read_b128 v[148:151], v247
	s_waitcnt lgkmcnt(0)
; #define GAS __attribute__((address_space(1)))
; DI unsigned pk2(float lo, float hi) { f32x2 v = {lo, hi}; bf16x2_t r = __builtin_convertvector(v, bf16x2_t); return __builtin_bit_cast(unsigned, r); }
; DI void unpack8(const u32x4 v, float (&f)[8]) { f[0] = bflo(v.x); f[1] = bfhi(v.x); f[2] = bflo(v.y); f[3] = bfhi(v.y); f[4] = bflo(v.z); f[5] = bfhi(v.z); f[6] = bflo(v.w); f[7] = bfhi(v.w); }
;     DI bool operator()(AccT& acc, const Unit& u, int wr, int wc, int fr, int fq) const {
;     ...
;                     float g0[8], g1[8], s[8]; unpack8(ga[bj][m], g0); unpack8(gb[bj][m], g1);
; #pragma unroll
;                     for (int e = 0; e < 8; ++e) { const float a = fmaxf(g0[e], 1e-20f); s[e] = (seg < 2) ? a * __builtin_amdgcn_rcpf(fmaxf(g1[e], 1e-20f)) : a; }
;                     f32x4 v0 = acc[ai][bj][m][0], v1 = acc[ai][bj][m][1];
; #pragma unroll
;                     for (int e = 0; e < 4; ++e) { v0[e] *= s[e]; v1[e] *= s[4 + e]; }
;                     acc[ai][bj][m][0] = v0; acc[ai][bj][m][1] = v1;
;                     if (seg == 2) { u32x4 w; w.x = pk2(v0[0], v0[1]); w.y = pk2(v0[2], v0[3]); w.z = pk2(v1[0], v1[1]); w.w = pk2(v1[2], v1[3]);
;                         *(GAS u32x4*)(out + (size_t)(row0 + ai * HALF + m * 16) * D + col0 + bj * HALF) = w; } }
	ds_write_b128 v246, v[176:179]
	ds_read_b128 v[176:179], v247
	ds_write_b128 v246, v[144:147]
	ds_read_b128 v[144:147], v247
	ds_write_b128 v246, v[172:175]
	ds_read_b128 v[172:175], v247
	ds_write_b128 v246, v[140:143]
	ds_read_b128 v[140:143], v247
	ds_write_b128 v246, v[168:171]
	ds_read_b128 v[168:171], v247
	ds_write_b128 v246, v[136:139]
	ds_read_b128 v[136:139], v247
	s_waitcnt lgkmcnt(0)
	ds_write_b128 v246, v[164:167]
	ds_read_b128 v[164:167], v247
	ds_write_b128 v246, v[132:135]
	ds_read_b128 v[132:135], v247
	ds_write_b128 v246, v[160:163]
	ds_read_b128 v[160:163], v247
	ds_write_b128 v246, v[128:131]
	ds_read_b128 v[128:131], v247
	s_waitcnt lgkmcnt(0)
	v_lshlrev_b32_e32 v223, 16, v196
	v_max_f32_e32 v223, v223, v223
	v_max_f32_e32 v223, 0x1e3ce508, v223
	v_rcp_f32_e32 v223, v223
	v_lshlrev_b32_e32 v217, 16, v188
	v_and_b32_e32 v196, 0xffff0000, v196
	v_max_f32_e32 v217, v217, v217
	v_max_f32_e32 v196, v196, v196
	v_lshlrev_b32_e32 v236, 16, v197
	v_max_f32_e32 v217, 0x1e3ce508, v217
	v_cndmask_b32_e64 v223, 1.0, v223, s[6:7]
	v_max_f32_e32 v196, 0x1e3ce508, v196
	v_rcp_f32_e32 v196, v196
	v_mul_f32_e32 v217, v217, v223
	v_max_f32_e32 v223, v236, v236
	v_max_f32_e32 v223, 0x1e3ce508, v223
	v_and_b32_e32 v188, 0xffff0000, v188
	v_rcp_f32_e32 v223, v223
	v_max_f32_e32 v188, v188, v188
	v_lshlrev_b32_e32 v218, 16, v189
	v_and_b32_e32 v197, 0xffff0000, v197
	v_max_f32_e32 v188, 0x1e3ce508, v188
	v_cndmask_b32_e64 v196, 1.0, v196, s[6:7]
	v_mul_f32_e32 v188, v188, v196
	v_max_f32_e32 v196, v218, v218
	v_max_f32_e32 v197, v197, v197
	v_lshlrev_b32_e32 v237, 16, v198
	v_max_f32_e32 v196, 0x1e3ce508, v196
	v_cndmask_b32_e64 v218, 1.0, v223, s[6:7]
	v_max_f32_e32 v197, 0x1e3ce508, v197
	v_rcp_f32_e32 v197, v197
	v_mul_f32_e32 v196, v196, v218
	v_max_f32_e32 v218, v237, v237
	v_max_f32_e32 v218, 0x1e3ce508, v218
	v_and_b32_e32 v189, 0xffff0000, v189
	v_rcp_f32_e32 v218, v218
	v_max_f32_e32 v189, v189, v189
	v_lshlrev_b32_e32 v219, 16, v190
	v_and_b32_e32 v198, 0xffff0000, v198
	v_max_f32_e32 v189, 0x1e3ce508, v189
	v_cndmask_b32_e64 v197, 1.0, v197, s[6:7]
	v_mul_f32_e32 v189, v189, v197
	v_max_f32_e32 v197, v219, v219
	v_max_f32_e32 v198, v198, v198
	v_lshlrev_b32_e32 v238, 16, v199
	v_and_b32_e32 v199, 0xffff0000, v199
	v_max_f32_e32 v197, 0x1e3ce508, v197
	v_cndmask_b32_e64 v218, 1.0, v218, s[6:7]
	v_max_f32_e32 v198, 0x1e3ce508, v198
	v_rcp_f32_e32 v198, v198
	v_mul_f32_e32 v197, v197, v218
	v_max_f32_e32 v218, v238, v238
	v_max_f32_e32 v199, v199, v199
	v_max_f32_e32 v218, 0x1e3ce508, v218
	v_max_f32_e32 v199, 0x1e3ce508, v199
	v_and_b32_e32 v190, 0xffff0000, v190
	v_rcp_f32_e32 v218, v218
	v_rcp_f32_e32 v199, v199
	v_max_f32_e32 v190, v190, v190
	v_lshlrev_b32_e32 v221, 16, v191
	v_and_b32_e32 v191, 0xffff0000, v191
	v_max_f32_e32 v190, 0x1e3ce508, v190
	v_cndmask_b32_e64 v198, 1.0, v198, s[6:7]
	v_mul_f32_e32 v190, v190, v198
	v_max_f32_e32 v198, v221, v221
	v_max_f32_e32 v191, v191, v191
	v_max_f32_e32 v198, 0x1e3ce508, v198
	v_cndmask_b32_e64 v218, 1.0, v218, s[6:7]
	v_max_f32_e32 v191, 0x1e3ce508, v191
	v_cndmask_b32_e64 v199, 1.0, v199, s[6:7]
	v_mul_f32_e32 v198, v198, v218
	v_mul_f32_e32 v191, v191, v199
	v_mul_f32_e32 v125, v125, v188
	v_mul_f32_e32 v127, v127, v189
	v_lshlrev_b64 v[188:189], 12, v[212:213]
	v_mul_f32_e32 v124, v124, v217
	v_mul_f32_e32 v120, v120, v197
	v_mul_f32_e32 v121, v121, v190
	v_mul_f32_e32 v126, v126, v196
	v_mul_f32_e32 v122, v122, v198
	v_mul_f32_e32 v123, v123, v191
	v_lshl_add_u64 v[218:219], s[10:11], 0, v[188:189]
	s_cbranch_scc1 .LBB0_1190
	v_cvt_pk_bf16_f32 v188, v124, v125
	v_cvt_pk_bf16_f32 v189, v126, v127
	v_cvt_pk_bf16_f32 v190, v120, v121
	v_cvt_pk_bf16_f32 v191, v122, v123
	v_lshl_add_u64 v[196:197], v[210:211], 1, v[218:219]
	global_store_dwordx4 v[196:197], v[188:191], off

; #define GAS __attribute__((address_space(1)))
;     DI bool operator()(AccT& acc, const Unit& u, int wr, int wc, int fr, int fq) const {
;     ...
;         for (int ai = 0; ai < 2; ++ai) {
;             u32x4 ga[2][4], gb[2][4];
; #pragma unroll
;             for (int bj = 0; bj < 2; ++bj)
; #pragma unroll
;                 for (int m = 0; m < 4; ++m) { const bf16* zr = Z + (size_t)(row0 + ai * HALF + m * 16) * ZP + ZC_GATE + col0 + bj * HALF;
;                     ga[bj][m] = *(const GAS u32x4*)(zr + seg * D); gb[bj][m] = *(const GAS u32x4*)(zr + (seg < 2 ? seg + 1 : seg) * D); }
;             __builtin_amdgcn_sched_barrier(0);
.LBB0_1204:
	v_add_u32_e32 v220, 0x80, v212
	s_nop 0
	v_mov_b64_e32 v[128:129], s[8:9]
	v_add_u32_e32 v218, 0x90, v212
	v_add_u32_e32 v216, 0xa0, v212
	v_add_u32_e32 v212, 0xb0, v212
	v_mad_i64_i32 v[130:131], s[0:1], v220, s15, v[128:129]
	v_mad_i64_i32 v[134:135], s[0:1], v218, s15, v[128:129]
	v_mad_i64_i32 v[138:139], s[0:1], v216, s15, v[128:129]
	v_mad_i64_i32 v[128:129], s[0:1], v212, s15, v[128:129]
	v_lshl_add_u64 v[130:131], v[130:131], 0, v[214:215]
	s_mov_b64 s[34:35], 0x27e0
	v_lshl_add_u64 v[134:135], v[134:135], 0, v[214:215]
	v_lshl_add_u64 v[138:139], v[138:139], 0, v[214:215]
	v_lshl_add_u64 v[128:129], v[128:129], 0, v[214:215]
	v_lshl_add_u64 v[130:131], v[130:131], 0, s[34:35]
	v_lshl_add_u64 v[134:135], v[134:135], 0, s[34:35]
	v_lshl_add_u64 v[138:139], v[138:139], 0, s[34:35]
	v_lshl_add_u64 v[128:129], v[128:129], 0, s[34:35]
	v_lshl_add_u64 v[132:133], v[130:131], 0, s[30:31]
	v_lshl_add_u64 v[130:131], v[130:131], 0, s[26:27]
	v_lshl_add_u64 v[136:137], v[134:135], 0, s[30:31]
	v_lshl_add_u64 v[134:135], v[134:135], 0, s[26:27]
	v_lshl_add_u64 v[140:141], v[138:139], 0, s[30:31]
	v_lshl_add_u64 v[138:139], v[138:139], 0, s[26:27]
	v_lshl_add_u64 v[160:161], v[128:129], 0, s[30:31]
	v_lshl_add_u64 v[128:129], v[128:129], 0, s[26:27]
	v_lshl_add_u64 v[242:243], v[132:133], 0, v[240:241]
	global_load_dwordx4 v[188:191], v[242:243], off
	v_lshl_add_u64 v[244:245], v[132:133], 0, v[240:241]
	global_load_dwordx4 v[156:159], v[244:245], off offset:256
	v_lshl_add_u64 v[242:243], v[130:131], 0, v[240:241]
	global_load_dwordx4 v[196:199], v[242:243], off
	v_lshl_add_u64 v[244:245], v[130:131], 0, v[240:241]
	global_load_dwordx4 v[152:155], v[244:245], off offset:256
	v_lshl_add_u64 v[242:243], v[136:137], 0, v[240:241]
	global_load_dwordx4 v[180:183], v[242:243], off
	v_lshl_add_u64 v[244:245], v[136:137], 0, v[240:241]
	global_load_dwordx4 v[148:151], v[244:245], off offset:256
	v_lshl_add_u64 v[242:243], v[134:135], 0, v[240:241]
	global_load_dwordx4 v[176:179], v[242:243], off
	v_lshl_add_u64 v[244:245], v[134:135], 0, v[240:241]
	global_load_dwordx4 v[144:147], v[244:245], off offset:256
	v_lshl_add_u64 v[242:243], v[140:141], 0, v[240:241]
	global_load_dwordx4 v[172:175], v[242:243], off
	s_nop 0
	v_lshl_add_u64 v[244:245], v[140:141], 0, v[240:241]
	global_load_dwordx4 v[140:143], v[244:245], off offset:256
	s_nop 0
	v_lshl_add_u64 v[242:243], v[138:139], 0, v[240:241]
	global_load_dwordx4 v[168:171], v[242:243], off
	s_nop 0
	v_lshl_add_u64 v[244:245], v[138:139], 0, v[240:241]
	global_load_dwordx4 v[136:139], v[244:245], off offset:256
	s_nop 0
	v_lshl_add_u64 v[242:243], v[160:161], 0, v[240:241]
	global_load_dwordx4 v[164:167], v[242:243], off
	v_lshl_add_u64 v[244:245], v[160:161], 0, v[240:241]
	global_load_dwordx4 v[132:135], v[244:245], off offset:256
	s_nop 0
	v_lshl_add_u64 v[242:243], v[128:129], 0, v[240:241]
	global_load_dwordx4 v[160:163], v[242:243], off
	s_nop 0
	v_lshl_add_u64 v[244:245], v[128:129], 0, v[240:241]
	global_load_dwordx4 v[128:131], v[244:245], off offset:256
	v_ashrrev_i32_e32 v221, 31, v220
	s_waitcnt vmcnt(0)
	ds_write_b128 v246, v[188:191]
	ds_read_b128 v[188:191], v247
	ds_write_b128 v246, v[156:159]
	ds_read_b128 v[156:159], v247
	ds_write_b128 v246, v[196:199]
	ds_read_b128 v[196:199], v247
	ds_write_b128 v246, v[152:155]
	ds_read_b128 v[152:155], v247
	ds_write_b128 v246, v[180:183]
	ds_read_b128 v[180:183], v247
	ds_write_b128 v246, v[148:151]
	ds_read_b128 v[148:151], v247
	s_waitcnt lgkmcnt(0)
; #define GAS __attribute__((address_space(1)))
; DI unsigned pk2(float lo, float hi) { f32x2 v = {lo, hi}; bf16x2_t r = __builtin_convertvector(v, bf16x2_t); return __builtin_bit_cast(unsigned, r); }
; DI void unpack8(const u32x4 v, float (&f)[8]) { f[0] = bflo(v.x); f[1] = bfhi(v.x); f[2] = bflo(v.y); f[3] = bfhi(v.y); f[4] = bflo(v.z); f[5] = bfhi(v.z); f[6] = bflo(v.w); f[7] = bfhi(v.w); }
;     DI bool operator()(AccT& acc, const Unit& u, int wr, int wc, int fr, int fq) const {
;     ...
;                 for (int m = 0; m < 4; ++m) { const bf16* zr = Z + (size_t)(row0 + ai * HALF + m * 16) * ZP + ZC_GATE + col0 + bj * HALF;
;                     ga[bj][m] = *(const GAS u32x4*)(zr + seg * D); gb[bj][m] = *(const GAS u32x4*)(zr + (seg < 2 ? seg + 1 : seg) * D); }
;             __builtin_amdgcn_sched_barrier(0);
; #pragma unroll
;             for (int bj = 0; bj < 2; ++bj)
; #pragma unroll
;                 for (int m = 0; m < 4; ++m) {
;                     float g0[8], g1[8], s[8]; unpack8(ga[bj][m], g0); unpack8(gb[bj][m], g1);
; #pragma unroll
;                     for (int e = 0; e < 8; ++e) { const float a = fmaxf(g0[e], 1e-20f); s[e] = (seg < 2) ? a * __builtin_amdgcn_rcpf(fmaxf(g1[e], 1e-20f)) : a; }
;                     f32x4 v0 = acc[ai][bj][m][0], v1 = acc[ai][bj][m][1];
; #pragma unroll
;                     for (int e = 0; e < 4; ++e) { v0[e] *= s[e]; v1[e] *= s[4 + e]; }
;                     acc[ai][bj][m][0] = v0; acc[ai][bj][m][1] = v1;
;                     if (seg == 2) { u32x4 w; w.x = pk2(v0[0], v0[1]); w.y = pk2(v0[2], v0[3]); w.z = pk2(v1[0], v1[1]); w.w = pk2(v1[2], v1[3]);
;                         *(GAS u32x4*)(out + (size_t)(row0 + ai * HALF + m * 16) * D + col0 + bj * HALF) = w; } }
	ds_write_b128 v246, v[176:179]
	ds_read_b128 v[176:179], v247
	ds_write_b128 v246, v[144:147]
	ds_read_b128 v[144:147], v247
	ds_write_b128 v246, v[172:175]
	ds_read_b128 v[172:175], v247
	ds_write_b128 v246, v[140:143]
	ds_read_b128 v[140:143], v247
	ds_write_b128 v246, v[168:171]
	ds_read_b128 v[168:171], v247
	ds_write_b128 v246, v[136:139]
	ds_read_b128 v[136:139], v247
	s_waitcnt lgkmcnt(0)
	ds_write_b128 v246, v[164:167]
	ds_read_b128 v[164:167], v247
	ds_write_b128 v246, v[132:135]
	ds_read_b128 v[132:135], v247
	ds_write_b128 v246, v[160:163]
	ds_read_b128 v[160:163], v247
	ds_write_b128 v246, v[128:131]
	ds_read_b128 v[128:131], v247
	s_waitcnt lgkmcnt(0)
	v_lshlrev_b32_e32 v219, 16, v196
	v_max_f32_e32 v219, v219, v219
	v_max_f32_e32 v219, 0x1e3ce508, v219
	v_rcp_f32_e32 v219, v219
	v_lshlrev_b32_e32 v213, 16, v188
	v_and_b32_e32 v196, 0xffff0000, v196
	v_max_f32_e32 v213, v213, v213
	v_max_f32_e32 v196, v196, v196
	v_lshlrev_b32_e32 v222, 16, v197
	v_max_f32_e32 v213, 0x1e3ce508, v213
	v_cndmask_b32_e64 v219, 1.0, v219, s[6:7]
	v_max_f32_e32 v196, 0x1e3ce508, v196
	v_rcp_f32_e32 v196, v196
	v_mul_f32_e32 v213, v213, v219
	v_max_f32_e32 v219, v222, v222
	v_max_f32_e32 v219, 0x1e3ce508, v219
	v_and_b32_e32 v188, 0xffff0000, v188
	v_rcp_f32_e32 v219, v219
	v_max_f32_e32 v188, v188, v188
	v_lshlrev_b32_e32 v214, 16, v189
	v_and_b32_e32 v197, 0xffff0000, v197
	v_max_f32_e32 v188, 0x1e3ce508, v188
	v_cndmask_b32_e64 v196, 1.0, v196, s[6:7]
	v_mul_f32_e32 v188, v188, v196
	v_max_f32_e32 v196, v214, v214
	v_max_f32_e32 v197, v197, v197
	v_lshlrev_b32_e32 v223, 16, v198
	v_max_f32_e32 v196, 0x1e3ce508, v196
	v_cndmask_b32_e64 v214, 1.0, v219, s[6:7]
	v_max_f32_e32 v197, 0x1e3ce508, v197
	v_rcp_f32_e32 v197, v197
	v_mul_f32_e32 v196, v196, v214
	v_max_f32_e32 v214, v223, v223
	v_max_f32_e32 v214, 0x1e3ce508, v214
	v_and_b32_e32 v189, 0xffff0000, v189
	v_rcp_f32_e32 v214, v214
	v_max_f32_e32 v189, v189, v189
	v_lshlrev_b32_e32 v215, 16, v190
	v_and_b32_e32 v198, 0xffff0000, v198
	v_max_f32_e32 v189, 0x1e3ce508, v189
	v_cndmask_b32_e64 v197, 1.0, v197, s[6:7]
	v_mul_f32_e32 v189, v189, v197
	v_max_f32_e32 v197, v215, v215
	v_max_f32_e32 v198, v198, v198
	v_lshlrev_b32_e32 v236, 16, v199
	v_and_b32_e32 v199, 0xffff0000, v199
	v_max_f32_e32 v197, 0x1e3ce508, v197
	v_cndmask_b32_e64 v214, 1.0, v214, s[6:7]
	v_max_f32_e32 v198, 0x1e3ce508, v198
	v_rcp_f32_e32 v198, v198
	v_mul_f32_e32 v197, v197, v214
	v_max_f32_e32 v214, v236, v236
	v_max_f32_e32 v199, v199, v199
	v_max_f32_e32 v214, 0x1e3ce508, v214
	v_max_f32_e32 v199, 0x1e3ce508, v199
	v_and_b32_e32 v190, 0xffff0000, v190
	v_rcp_f32_e32 v214, v214
	v_rcp_f32_e32 v199, v199
	v_max_f32_e32 v190, v190, v190
	v_lshlrev_b32_e32 v217, 16, v191
	v_and_b32_e32 v191, 0xffff0000, v191
	v_max_f32_e32 v190, 0x1e3ce508, v190
	v_cndmask_b32_e64 v198, 1.0, v198, s[6:7]
	v_mul_f32_e32 v190, v190, v198
	v_max_f32_e32 v198, v217, v217
	v_max_f32_e32 v191, v191, v191
	v_max_f32_e32 v198, 0x1e3ce508, v198
	v_cndmask_b32_e64 v214, 1.0, v214, s[6:7]
	v_max_f32_e32 v191, 0x1e3ce508, v191
	v_cndmask_b32_e64 v199, 1.0, v199, s[6:7]
	v_mul_f32_e32 v198, v198, v214
	v_mul_f32_e32 v191, v191, v199
	v_mul_f32_e32 v61, v61, v188
	v_mul_f32_e32 v63, v63, v189
	v_lshlrev_b64 v[188:189], 12, v[220:221]
	v_mul_f32_e32 v60, v60, v213
	v_mul_f32_e32 v56, v56, v197
	v_mul_f32_e32 v57, v57, v190
	v_mul_f32_e32 v62, v62, v196
	v_mul_f32_e32 v58, v58, v198
	v_mul_f32_e32 v59, v59, v191
	s_and_b64 vcc, exec, s[40:41]
	v_lshl_add_u64 v[214:215], s[10:11], 0, v[188:189]
	s_cbranch_vccnz .LBB0_1206
	v_cvt_pk_bf16_f32 v188, v60, v61
	v_cvt_pk_bf16_f32 v189, v62, v63
	v_cvt_pk_bf16_f32 v190, v56, v57
	v_cvt_pk_bf16_f32 v191, v58, v59
	v_lshl_add_u64 v[196:197], v[210:211], 1, v[214:215]
	global_store_dwordx4 v[196:197], v[188:191], off

; #define GAS __attribute__((address_space(1)))
; #define PG8_STAGE(bufoff, gbase, voff) do { _Pragma("unroll") for (int _i = 0; _i < 2; ++_i) \
;         __builtin_amdgcn_global_load_lds((const unsigned*)((const char*)(gbase) + (voff)[_i]), (LAS unsigned*)(lds + (bufoff) + ldsw + _i * 8192), 16, 0, 0); } while (0)
; #define PG8_WAIT_V(n) asm volatile("s_waitcnt vmcnt(" #n ")" ::: "memory")
; #define PG8_BAR __builtin_amdgcn_s_barrier()
; template <class Epi, class Sched>
; DI void gemm_phase(LAS unsigned char* lds, const int wv, const int lda, const int ldb, const Sched& S, const Epi& E) {
;     ...
;     PG8_STAGE(PG8_SB(0, 0), cB, voffB); PG8_STAGE(PG8_SB(0, 1), cB + hstepB, voffB); PG8_STAGE(PG8_SA(0, 0), cA, voffA); PG8_STAGE(PG8_SA(0, 1), cA + hstepA, voffA);
;     if (wr == 1) PG8_BAR;
;     PG8_WAIT_V(2); PG8_BAR;
;     PG8_STAGE(PG8_SB(1, 0), cB + kstep, voffB); PG8_STAGE(PG8_SA(1, 0), cA + kstep, voffA); PG8_STAGE(PG8_SB(1, 1), cB + hstepB + kstep, voffB);
;     PG8_WAIT_V(6); PG8_BAR;
;     DI bool operator()(AccT& acc, const Unit& u, int wr, int wc, int fr, int fq) const {
;     ...
;             for (int m = 0; m < 4; ++m) { const bf16* rowp = xb + (size_t)(row0 + ai * HALF + m * 16) * XP + col0;
; #pragma unroll
;                 for (int bj = 0; bj < 2; ++bj) xv[m][bj] = *(const GAS u32x4*)(rowp + bj * HALF); }
.LBB0_1289:
	v_and_b32_e32 v15, 15, v14
	v_bfe_u32 v14, v14, 4, 2
	v_lshlrev_b32_e32 v17, 4, v14
	v_lshl_or_b32 v154, s1, 6, v15
	v_lshl_or_b32 v17, v15, 6, v17
	v_lshlrev_b32_e32 v15, 2, v15
	s_and_b32 s7, s0, 3
	s_lshl_b32 s0, s1, 13
	v_and_b32_e32 v18, 32, v15
	s_add_i32 m0, s27, 0x18000
	v_lshl_add_u64 v[6:7], v[6:7], 0, s[28:29]
	v_bitop3_b32 v19, v17, s0, v18 bitop3:0xde
	s_lshl_b32 s0, s7, 12
	s_waitcnt vmcnt(2)
	s_barrier
	global_load_lds_dwordx4 v[6:7], off
	v_lshl_add_u64 v[4:5], v[4:5], 0, s[28:29]
	s_add_i32 m0, s27, 0x1a000
	s_add_i32 s45, s27, 0x8000
	s_add_i32 s46, s27, 0xa000
	v_bitop3_b32 v155, v17, s0, v18 bitop3:0xde
	global_load_lds_dwordx4 v[4:5], off
	v_lshl_add_u64 v[0:1], v[0:1], 0, s[28:29]
	s_mov_b32 m0, s45
	s_add_u32 s0, s34, 0x80080
	global_load_lds_dwordx4 v[0:1], off
	v_lshl_add_u64 v[0:1], v[2:3], 0, s[28:29]
	s_mov_b32 m0, s46
	s_addc_u32 s1, s35, 0
	global_load_lds_dwordx4 v[0:1], off
	s_add_i32 m0, s27, 0x1c000
	v_lshl_add_u64 v[0:1], s[0:1], 0, v[184:185]
	global_load_lds_dwordx4 v[0:1], off
	v_lshl_add_u64 v[0:1], s[0:1], 0, v[136:137]
	s_add_i32 m0, s27, 0x1e000
	s_movk_i32 s0, 0x80
	global_load_lds_dwordx4 v[0:1], off
	v_lshlrev_b32_e32 v0, 6, v14
	v_bitop3_b32 v157, v0, 64, v15 bitop3:0x36
	v_bitop3_b32 v158, v0, s0, v15 bitop3:0x36
	v_lshlrev_b32_e32 v0, 15, v8
	v_and_b32_e32 v0, 0xffff0000, v0
	v_lshl_add_u32 v0, v9, 12, v0
	v_and_b32_e32 v1, 1, v8
	s_cmpk_lt_u32 s6, 0x100
	v_lshl_or_b32 v0, v1, 6, v0
	s_cselect_b64 s[12:13], -1, 0
	s_ashr_i32 s48, s20, 31
	s_ashr_i32 s49, s17, 31
	s_lshl_b32 s0, s7, 2
	v_lshl_add_u32 v138, v10, 1, v0
	v_lshlrev_b32_e32 v0, 15, v11
	s_add_u32 s0, s10, s0
	v_and_b32_e32 v0, 0xffff0000, v0
	s_waitcnt vmcnt(6)
	s_addc_u32 s1, s11, 0
	v_lshl_add_u32 v0, v12, 12, v0
	v_and_b32_e32 v1, 1, v11
	v_lshlrev_b32_e32 v16, 3, v14
	s_add_u32 s50, s0, 0x49c28000
	v_lshl_or_b32 v0, v1, 6, v0
	v_lshl_or_b32 v156, s7, 5, v16
	s_mov_b32 s47, 0
	v_cmp_eq_u32_e64 s[4:5], 0, v14
	s_addc_u32 s51, s1, 0
	v_mov_b32_e32 v139, v185
	v_lshl_add_u32 v140, v13, 1, v0
	v_mov_b32_e32 v141, v185
	v_add_u32_e32 v159, 0, v19
	s_barrier
	v_mbcnt_lo_u32_b32 v248, -1, 0
	v_mbcnt_hi_u32_b32 v248, -1, v248
	s_lshl_b32 s98, s90, 10
	s_add_i32 s98, s98, 0x22000
	v_lshl_add_u32 v246, v248, 4, s98
	v_and_b32_e32 v249, 15, v248
	v_lshrrev_b32_e32 v242, 4, v248
	v_lshrrev_b32_e32 v243, 2, v249
	v_lshl_add_u32 v242, v243, 4, v242
	v_and_b32_e32 v243, 3, v249
	v_lshl_add_u32 v242, v243, 2, v242
	v_lshl_add_u32 v247, v242, 4, s98
	v_lshrrev_b32_e32 v242, 4, v248
	v_bfe_u32 v243, v248, 2, 2
	v_lshl_add_u32 v243, v242, 2, v243
	v_sub_u32_e32 v243, v243, v249
	v_and_b32_e32 v249, 3, v248
	v_sub_u32_e32 v249, v249, v242
	v_lshlrev_b32_e32 v249, 4, v249
	s_movk_i32 s98, 0x1000
	v_mad_i32_i24 v240, v243, s98, v249
	v_ashrrev_i32_e32 v241, 31, v240
	s_branch .LBB0_1292

; #define GAS __attribute__((address_space(1)))
; DI unsigned pk2(float lo, float hi) { f32x2 v = {lo, hi}; bf16x2_t r = __builtin_convertvector(v, bf16x2_t); return __builtin_bit_cast(unsigned, r); }
;     DI bool operator()(AccT& acc, const Unit& u, int wr, int wc, int fr, int fq) const {
;     ...
;             for (int m = 0; m < 4; ++m) { const bf16* rowp = xb + (size_t)(row0 + ai * HALF + m * 16) * XP + col0;
; #pragma unroll
;                 for (int bj = 0; bj < 2; ++bj) xv[m][bj] = *(const GAS u32x4*)(rowp + bj * HALF); }
;             __builtin_amdgcn_sched_barrier(0);
; #pragma unroll
;             for (int m = 0; m < 4; ++m) { bf16* rowp = xo + (size_t)(row0 + ai * HALF + m * 16) * XP + col0; float s = 0.f;
; #pragma unroll
;                 for (int bj = 0; bj < 2; ++bj) { const u32x4 x = xv[m][bj]; const f32x4 a0 = acc[ai][bj][m][0], a1 = acc[ai][bj][m][1];
;                     const float y0 = bflo(x.x) + a0[0], y1 = bfhi(x.x) + a0[1], y2 = bflo(x.y) + a0[2], y3 = bfhi(x.y) + a0[3], y4 = bflo(x.z) + a1[0], y5 = bfhi(x.z) + a1[1], y6 = bflo(x.w) + a1[2], y7 = bfhi(x.w) + a1[3];
;                     s += (y0 * y0 + y1 * y1) + (y2 * y2 + y3 * y3) + (y4 * y4 + y5 * y5) + (y6 * y6 + y7 * y7);
;                     u32x4 w; w.x = pk2(y0, y1); w.y = pk2(y2, y3); w.z = pk2(y4, y5); w.w = pk2(y6, y7);
;                     *(GAS u32x4*)(rowp + bj * HALF) = w; }
.LBB0_1302:
	v_lshl_or_b32 v128, s14, 8, v156
	v_lshl_add_u32 v148, s26, 8, v154
	v_ashrrev_i32_e32 v129, 31, v128
	v_lshlrev_b64 v[150:151], 1, v[128:129]
	v_ashrrev_i32_e32 v149, 31, v148
	v_or_b32_e32 v146, 16, v148
	v_lshl_add_u64 v[152:153], s[8:9], 0, v[150:151]
	v_lshlrev_b64 v[196:197], 12, v[148:149]
	v_ashrrev_i32_e32 v147, 31, v146
	v_or_b32_e32 v144, 32, v148
	v_lshl_add_u64 v[128:129], v[152:153], 0, v[196:197]
	v_lshlrev_b64 v[198:199], 12, v[146:147]
	v_ashrrev_i32_e32 v145, 31, v144
	v_or_b32_e32 v142, 48, v148
	v_lshl_add_u64 v[242:243], v[128:129], 0, v[240:241]
	global_load_dwordx4 v[160:163], v[242:243], off
	v_lshl_add_u64 v[244:245], v[128:129], 0, v[240:241]
	global_load_dwordx4 v[164:167], v[244:245], off offset:256
	v_lshl_add_u64 v[128:129], v[152:153], 0, v[198:199]
	v_lshlrev_b64 v[200:201], 12, v[144:145]
	v_ashrrev_i32_e32 v143, 31, v142
	v_lshl_add_u64 v[242:243], v[128:129], 0, v[240:241]
	global_load_dwordx4 v[168:171], v[242:243], off
	v_lshl_add_u64 v[244:245], v[128:129], 0, v[240:241]
	global_load_dwordx4 v[172:175], v[244:245], off offset:256
	v_lshl_add_u64 v[128:129], v[152:153], 0, v[200:201]
	v_lshlrev_b64 v[202:203], 12, v[142:143]
	v_lshl_add_u64 v[242:243], v[128:129], 0, v[240:241]
	global_load_dwordx4 v[176:179], v[242:243], off
	v_lshl_add_u64 v[244:245], v[128:129], 0, v[240:241]
	global_load_dwordx4 v[180:183], v[244:245], off offset:256
	v_lshl_add_u64 v[128:129], v[152:153], 0, v[202:203]
	v_lshl_add_u64 v[242:243], v[128:129], 0, v[240:241]
	global_load_dwordx4 v[188:191], v[242:243], off
	s_nop 0
	v_lshl_add_u64 v[244:245], v[128:129], 0, v[240:241]
	global_load_dwordx4 v[128:131], v[244:245], off offset:256
	s_waitcnt vmcnt(0)
	ds_write_b128 v246, v[160:163]
	ds_read_b128 v[160:163], v247
	ds_write_b128 v246, v[164:167]
	ds_read_b128 v[164:167], v247
	ds_write_b128 v246, v[168:171]
	ds_read_b128 v[168:171], v247
	ds_write_b128 v246, v[172:175]
	ds_read_b128 v[172:175], v247
	ds_write_b128 v246, v[176:179]
	ds_read_b128 v[176:179], v247
	ds_write_b128 v246, v[180:183]
	ds_read_b128 v[180:183], v247
	s_waitcnt lgkmcnt(0)
	ds_write_b128 v246, v[188:191]
	ds_read_b128 v[188:191], v247
	ds_write_b128 v246, v[128:131]
	ds_read_b128 v[128:131], v247
	s_waitcnt lgkmcnt(0)
	v_lshlrev_b32_e32 v204, 16, v160
	v_and_b32_e32 v205, 0xffff0000, v160
	v_lshlrev_b32_e32 v160, 16, v161
	v_and_b32_e32 v161, 0xffff0000, v161
	v_pk_add_f32 v[126:127], v[126:127], v[160:161]
	v_lshlrev_b32_e32 v160, 16, v162
	v_and_b32_e32 v161, 0xffff0000, v162
	v_pk_add_f32 v[160:161], v[120:121], v[160:161]
	v_lshlrev_b32_e32 v120, 16, v163
	v_and_b32_e32 v121, 0xffff0000, v163
	v_lshl_add_u64 v[196:197], s[8:9], 0, v[196:197]
	v_pk_add_f32 v[124:125], v[124:125], v[204:205]
	v_pk_add_f32 v[162:163], v[122:123], v[120:121]
	v_lshl_add_u64 v[196:197], v[196:197], 0, v[150:151]
	v_cvt_pk_bf16_f32 v120, v124, v125
	v_cvt_pk_bf16_f32 v121, v126, v127
	v_cvt_pk_bf16_f32 v122, v160, v161
	v_cvt_pk_bf16_f32 v123, v162, v163
	global_store_dwordx4 v[196:197], v[120:123], off
	v_pk_mul_f32 v[204:205], v[124:125], v[124:125]
	v_pk_mul_f32 v[206:207], v[126:127], v[126:127]
	v_lshlrev_b32_e32 v120, 16, v164
	v_and_b32_e32 v121, 0xffff0000, v164
	v_pk_add_f32 v[116:117], v[116:117], v[120:121]
	v_lshlrev_b32_e32 v120, 16, v165
	v_and_b32_e32 v121, 0xffff0000, v165
	v_pk_add_f32 v[118:119], v[118:119], v[120:121]
	v_lshlrev_b32_e32 v120, 16, v166
	v_and_b32_e32 v121, 0xffff0000, v166
	v_pk_add_f32 v[120:121], v[112:113], v[120:121]
	v_lshlrev_b32_e32 v112, 16, v167
	v_and_b32_e32 v113, 0xffff0000, v167
	v_pk_add_f32 v[122:123], v[114:115], v[112:113]
	v_pk_mul_f32 v[112:113], v[116:117], v[116:117]
	v_pk_mul_f32 v[114:115], v[118:119], v[118:119]
	v_add_f32_e32 v112, v112, v113
	v_add_f32_e32 v114, v114, v115
	v_pk_mul_f32 v[208:209], v[160:161], v[160:161]
	v_pk_mul_f32 v[124:125], v[120:121], v[120:121]
	v_add_f32_e32 v112, v112, v114
	v_add_f32_e32 v114, v206, v207
	v_add_f32_e32 v115, v204, v205
	v_pk_mul_f32 v[210:211], v[162:163], v[162:163]
	v_pk_mul_f32 v[126:127], v[122:123], v[122:123]
	v_add_f32_e32 v113, v124, v125
	v_add_f32_e32 v114, v115, v114
	v_add_f32_e32 v115, v208, v209
	v_add_f32_e32 v126, v126, v127
	v_add_f32_e32 v112, v113, v112
	v_add_f32_e32 v113, v210, v211
	v_add_f32_e32 v114, v115, v114
	v_add_f32_e32 v112, v126, v112
	v_add_f32_e32 v113, v113, v114
	v_add_f32_e32 v160, v113, v112
	v_cvt_pk_bf16_f32 v112, v116, v117
	v_cvt_pk_bf16_f32 v113, v118, v119
	v_cvt_pk_bf16_f32 v114, v120, v121
	v_cvt_pk_bf16_f32 v115, v122, v123
	global_store_dwordx4 v[196:197], v[112:115], off offset:256
	s_nop 1
	v_lshl_add_u64 v[112:113], s[8:9], 0, v[198:199]
	v_lshl_add_u64 v[116:117], v[112:113], 0, v[150:151]
	v_lshlrev_b32_e32 v112, 16, v168
	v_and_b32_e32 v113, 0xffff0000, v168
	v_pk_add_f32 v[108:109], v[108:109], v[112:113]
	v_lshlrev_b32_e32 v112, 16, v169
	v_and_b32_e32 v113, 0xffff0000, v169
	v_pk_add_f32 v[110:111], v[110:111], v[112:113]
	v_lshlrev_b32_e32 v112, 16, v170
	v_and_b32_e32 v113, 0xffff0000, v170
	v_pk_add_f32 v[104:105], v[104:105], v[112:113]
	v_lshlrev_b32_e32 v112, 16, v171
	v_and_b32_e32 v113, 0xffff0000, v171
	v_pk_add_f32 v[106:107], v[106:107], v[112:113]
	v_cvt_pk_bf16_f32 v112, v108, v109
	v_cvt_pk_bf16_f32 v113, v110, v111
	v_cvt_pk_bf16_f32 v114, v104, v105
	v_cvt_pk_bf16_f32 v115, v106, v107
	global_store_dwordx4 v[116:117], v[112:115], off
	s_nop 1
	v_lshlrev_b32_e32 v112, 16, v172
	v_and_b32_e32 v113, 0xffff0000, v172
	v_pk_add_f32 v[100:101], v[100:101], v[112:113]
	v_lshlrev_b32_e32 v112, 16, v173
	v_and_b32_e32 v113, 0xffff0000, v173
	v_pk_add_f32 v[102:103], v[102:103], v[112:113]
; #define GAS __attribute__((address_space(1)))
; DI unsigned pk2(float lo, float hi) { f32x2 v = {lo, hi}; bf16x2_t r = __builtin_convertvector(v, bf16x2_t); return __builtin_bit_cast(unsigned, r); }
;     DI bool operator()(AccT& acc, const Unit& u, int wr, int wc, int fr, int fq) const {
;     ...
;             for (int m = 0; m < 4; ++m) { const bf16* rowp = xb + (size_t)(row0 + ai * HALF + m * 16) * XP + col0;
; #pragma unroll
;                 for (int bj = 0; bj < 2; ++bj) xv[m][bj] = *(const GAS u32x4*)(rowp + bj * HALF); }
;             __builtin_amdgcn_sched_barrier(0);
; #pragma unroll
;             for (int m = 0; m < 4; ++m) { bf16* rowp = xo + (size_t)(row0 + ai * HALF + m * 16) * XP + col0; float s = 0.f;
; #pragma unroll
;                 for (int bj = 0; bj < 2; ++bj) { const u32x4 x = xv[m][bj]; const f32x4 a0 = acc[ai][bj][m][0], a1 = acc[ai][bj][m][1];
;                     const float y0 = bflo(x.x) + a0[0], y1 = bfhi(x.x) + a0[1], y2 = bflo(x.y) + a0[2], y3 = bfhi(x.y) + a0[3], y4 = bflo(x.z) + a1[0], y5 = bfhi(x.z) + a1[1], y6 = bflo(x.w) + a1[2], y7 = bfhi(x.w) + a1[3];
;                     s += (y0 * y0 + y1 * y1) + (y2 * y2 + y3 * y3) + (y4 * y4 + y5 * y5) + (y6 * y6 + y7 * y7);
;                     u32x4 w; w.x = pk2(y0, y1); w.y = pk2(y2, y3); w.z = pk2(y4, y5); w.w = pk2(y6, y7);
;                     *(GAS u32x4*)(rowp + bj * HALF) = w; }
	v_lshlrev_b32_e32 v112, 16, v174
	v_and_b32_e32 v113, 0xffff0000, v174
	v_pk_add_f32 v[112:113], v[92:93], v[112:113]
	v_lshlrev_b32_e32 v92, 16, v175
	v_and_b32_e32 v93, 0xffff0000, v175
	v_pk_add_f32 v[114:115], v[94:95], v[92:93]
	v_cvt_pk_bf16_f32 v92, v100, v101
	v_cvt_pk_bf16_f32 v93, v102, v103
	v_cvt_pk_bf16_f32 v94, v112, v113
	v_cvt_pk_bf16_f32 v95, v114, v115
	global_store_dwordx4 v[116:117], v[92:95], off offset:256
	s_nop 1
	v_lshl_add_u64 v[92:93], s[8:9], 0, v[200:201]
	v_lshl_add_u64 v[116:117], v[92:93], 0, v[150:151]
	v_lshlrev_b32_e32 v92, 16, v176
	v_and_b32_e32 v93, 0xffff0000, v176
	v_pk_add_f32 v[92:93], v[96:97], v[92:93]
	v_lshlrev_b32_e32 v96, 16, v178
	v_and_b32_e32 v97, 0xffff0000, v178
	v_lshlrev_b32_e32 v94, 16, v177
	v_and_b32_e32 v95, 0xffff0000, v177
	v_pk_add_f32 v[88:89], v[88:89], v[96:97]
	v_lshlrev_b32_e32 v96, 16, v179
	v_and_b32_e32 v97, 0xffff0000, v179
	v_pk_add_f32 v[94:95], v[98:99], v[94:95]
	v_pk_add_f32 v[90:91], v[90:91], v[96:97]
	v_cvt_pk_bf16_f32 v96, v92, v93
	v_cvt_pk_bf16_f32 v97, v94, v95
	v_cvt_pk_bf16_f32 v98, v88, v89
	v_cvt_pk_bf16_f32 v99, v90, v91
	global_store_dwordx4 v[116:117], v[96:99], off
	s_nop 1
	v_lshlrev_b32_e32 v96, 16, v180
	v_and_b32_e32 v97, 0xffff0000, v180
	v_pk_add_f32 v[84:85], v[84:85], v[96:97]
	v_lshlrev_b32_e32 v96, 16, v181
	v_and_b32_e32 v97, 0xffff0000, v181
	v_pk_add_f32 v[86:87], v[86:87], v[96:97]
	v_lshlrev_b32_e32 v96, 16, v182
	v_and_b32_e32 v97, 0xffff0000, v182
	v_pk_add_f32 v[96:97], v[76:77], v[96:97]
	v_lshlrev_b32_e32 v76, 16, v183
	v_and_b32_e32 v77, 0xffff0000, v183
	v_pk_add_f32 v[98:99], v[78:79], v[76:77]
	v_cvt_pk_bf16_f32 v76, v84, v85
	v_cvt_pk_bf16_f32 v77, v86, v87
	v_cvt_pk_bf16_f32 v78, v96, v97
	v_cvt_pk_bf16_f32 v79, v98, v99
	global_store_dwordx4 v[116:117], v[76:79], off offset:256
	s_nop 1
	v_lshl_add_u64 v[76:77], s[8:9], 0, v[202:203]
	v_lshl_add_u64 v[124:125], v[76:77], 0, v[150:151]
	v_lshlrev_b32_e32 v76, 16, v188
	v_and_b32_e32 v77, 0xffff0000, v188
	v_pk_add_f32 v[76:77], v[80:81], v[76:77]
	v_lshlrev_b32_e32 v80, 16, v190
	v_and_b32_e32 v81, 0xffff0000, v190
	v_lshlrev_b32_e32 v78, 16, v189
	v_and_b32_e32 v79, 0xffff0000, v189
	v_pk_add_f32 v[80:81], v[72:73], v[80:81]
	v_lshlrev_b32_e32 v72, 16, v191
	v_and_b32_e32 v73, 0xffff0000, v191
	v_pk_add_f32 v[78:79], v[82:83], v[78:79]
	v_pk_add_f32 v[82:83], v[74:75], v[72:73]
	v_cvt_pk_bf16_f32 v72, v76, v77
	v_cvt_pk_bf16_f32 v73, v78, v79
	v_cvt_pk_bf16_f32 v74, v80, v81
	v_cvt_pk_bf16_f32 v75, v82, v83
	global_store_dwordx4 v[124:125], v[72:75], off
	s_nop 1
	v_lshlrev_b32_e32 v72, 16, v128
	v_and_b32_e32 v73, 0xffff0000, v128
	v_pk_add_f32 v[116:117], v[68:69], v[72:73]
	v_lshlrev_b32_e32 v68, 16, v129
	v_and_b32_e32 v69, 0xffff0000, v129
	v_pk_add_f32 v[118:119], v[70:71], v[68:69]
	v_lshlrev_b32_e32 v68, 16, v130
	v_and_b32_e32 v69, 0xffff0000, v130
	v_pk_add_f32 v[120:121], v[64:65], v[68:69]
	v_lshlrev_b32_e32 v64, 16, v131
	v_and_b32_e32 v65, 0xffff0000, v131
	v_pk_add_f32 v[122:123], v[66:67], v[64:65]
	v_cvt_pk_bf16_f32 v64, v116, v117
	v_cvt_pk_bf16_f32 v65, v118, v119
	v_cvt_pk_bf16_f32 v66, v120, v121
	v_cvt_pk_bf16_f32 v67, v122, v123
	global_store_dwordx4 v[124:125], v[64:67], off offset:256
	v_add_u32_e32 v74, 0x80, v148
	v_ashrrev_i32_e32 v75, 31, v74
	v_add_u32_e32 v72, 0x90, v148
	v_lshlrev_b64 v[182:183], 12, v[74:75]
	v_ashrrev_i32_e32 v73, 31, v72
	v_add_u32_e32 v70, 0xa0, v148
	v_lshl_add_u64 v[64:65], v[152:153], 0, v[182:183]
	v_lshlrev_b64 v[188:189], 12, v[72:73]
	v_ashrrev_i32_e32 v71, 31, v70
	v_add_u32_e32 v68, 0xb0, v148
	v_lshl_add_u64 v[242:243], v[64:65], 0, v[240:241]
	global_load_dwordx4 v[124:127], v[242:243], off
	v_lshl_add_u64 v[244:245], v[64:65], 0, v[240:241]
	global_load_dwordx4 v[128:131], v[244:245], off offset:256
	v_lshl_add_u64 v[64:65], v[152:153], 0, v[188:189]
	v_lshlrev_b64 v[190:191], 12, v[70:71]
	v_ashrrev_i32_e32 v69, 31, v68
	v_lshl_add_u64 v[242:243], v[64:65], 0, v[240:241]
	global_load_dwordx4 v[162:165], v[242:243], off
	v_lshl_add_u64 v[244:245], v[64:65], 0, v[240:241]
	global_load_dwordx4 v[166:169], v[244:245], off offset:256
	v_lshl_add_u64 v[64:65], v[152:153], 0, v[190:191]
	v_lshlrev_b64 v[196:197], 12, v[68:69]
	v_lshl_add_u64 v[242:243], v[64:65], 0, v[240:241]
	global_load_dwordx4 v[170:173], v[242:243], off
	v_lshl_add_u64 v[244:245], v[64:65], 0, v[240:241]
	global_load_dwordx4 v[174:177], v[244:245], off offset:256
	v_lshl_add_u64 v[64:65], v[152:153], 0, v[196:197]
	v_lshl_add_u64 v[242:243], v[64:65], 0, v[240:241]
	global_load_dwordx4 v[178:181], v[242:243], off
	s_nop 0
	v_lshl_add_u64 v[244:245], v[64:65], 0, v[240:241]
	global_load_dwordx4 v[64:67], v[244:245], off offset:256
	v_lshl_add_u64 v[152:153], s[8:9], 0, v[182:183]
	s_waitcnt vmcnt(0)
	ds_write_b128 v246, v[124:127]
	ds_read_b128 v[124:127], v247
	ds_write_b128 v246, v[128:131]
	ds_read_b128 v[128:131], v247
	ds_write_b128 v246, v[162:165]
	ds_read_b128 v[162:165], v247
	ds_write_b128 v246, v[166:169]
	ds_read_b128 v[166:169], v247
	ds_write_b128 v246, v[170:173]
	ds_read_b128 v[170:173], v247
	ds_write_b128 v246, v[174:177]
	ds_read_b128 v[174:177], v247
	s_waitcnt lgkmcnt(0)
	ds_write_b128 v246, v[178:181]
	ds_read_b128 v[178:181], v247
	ds_write_b128 v246, v[64:67]
	ds_read_b128 v[64:67], v247
	s_waitcnt lgkmcnt(0)
; #define GAS __attribute__((address_space(1)))
; DI unsigned pk2(float lo, float hi) { f32x2 v = {lo, hi}; bf16x2_t r = __builtin_convertvector(v, bf16x2_t); return __builtin_bit_cast(unsigned, r); }
;     DI bool operator()(AccT& acc, const Unit& u, int wr, int wc, int fr, int fq) const {
;     ...
;             for (int m = 0; m < 4; ++m) { bf16* rowp = xo + (size_t)(row0 + ai * HALF + m * 16) * XP + col0; float s = 0.f;
; #pragma unroll
;                 for (int bj = 0; bj < 2; ++bj) { const u32x4 x = xv[m][bj]; const f32x4 a0 = acc[ai][bj][m][0], a1 = acc[ai][bj][m][1];
;                     const float y0 = bflo(x.x) + a0[0], y1 = bfhi(x.x) + a0[1], y2 = bflo(x.y) + a0[2], y3 = bfhi(x.y) + a0[3], y4 = bflo(x.z) + a1[0], y5 = bfhi(x.z) + a1[1], y6 = bflo(x.w) + a1[2], y7 = bfhi(x.w) + a1[3];
;                     s += (y0 * y0 + y1 * y1) + (y2 * y2 + y3 * y3) + (y4 * y4 + y5 * y5) + (y6 * y6 + y7 * y7);
;                     u32x4 w; w.x = pk2(y0, y1); w.y = pk2(y2, y3); w.z = pk2(y4, y5); w.w = pk2(y6, y7);
;                     *(GAS u32x4*)(rowp + bj * HALF) = w; }
;                 ps[ai][m] = s; }
;             __builtin_amdgcn_sched_barrier(0);
;         }
;         { int a16 = ((fr + 16 * fq) ^ 16) << 2, a32 = ((fr + 16 * fq) ^ 32) << 2;
; #pragma unroll
;           for (int ai = 0; ai < 2; ++ai)
; #pragma unroll
;               for (int m = 0; m < 4; ++m) { float s = ps[ai][m];
;                   s += __builtin_bit_cast(float, __builtin_amdgcn_ds_bpermute(a16, __builtin_bit_cast(int, s)));
;                   s += __builtin_bit_cast(float, __builtin_amdgcn_ds_bpermute(a32, __builtin_bit_cast(int, s)));
;                   if (fq == 0) ssq[(size_t)(row0 + ai * HALF + m * 16) * 32 + u.pn * 4 + wc] = s; } }
	v_lshlrev_b32_e32 v182, 16, v124
	v_and_b32_e32 v183, 0xffff0000, v124
	v_lshlrev_b32_e32 v124, 16, v125
	v_and_b32_e32 v125, 0xffff0000, v125
	v_pk_add_f32 v[62:63], v[62:63], v[124:125]
	v_lshlrev_b32_e32 v124, 16, v126
	v_and_b32_e32 v125, 0xffff0000, v126
	v_pk_add_f32 v[56:57], v[56:57], v[124:125]
	v_lshlrev_b32_e32 v124, 16, v127
	v_and_b32_e32 v125, 0xffff0000, v127
	v_pk_add_f32 v[60:61], v[60:61], v[182:183]
	v_pk_add_f32 v[58:59], v[58:59], v[124:125]
	v_lshl_add_u64 v[152:153], v[152:153], 0, v[150:151]
	v_cvt_pk_bf16_f32 v124, v60, v61
	v_cvt_pk_bf16_f32 v125, v62, v63
	v_cvt_pk_bf16_f32 v126, v56, v57
	v_cvt_pk_bf16_f32 v127, v58, v59
	global_store_dwordx4 v[152:153], v[124:127], off
	s_waitcnt vmcnt(7)
	s_nop 0
	v_lshlrev_b32_e32 v124, 16, v128
	v_and_b32_e32 v125, 0xffff0000, v128
	v_pk_add_f32 v[52:53], v[52:53], v[124:125]
	v_lshlrev_b32_e32 v124, 16, v129
	v_and_b32_e32 v125, 0xffff0000, v129
	v_pk_add_f32 v[54:55], v[54:55], v[124:125]
	v_lshlrev_b32_e32 v124, 16, v130
	v_and_b32_e32 v125, 0xffff0000, v130
	v_pk_add_f32 v[124:125], v[44:45], v[124:125]
	v_lshlrev_b32_e32 v44, 16, v131
	v_and_b32_e32 v45, 0xffff0000, v131
	v_pk_add_f32 v[126:127], v[46:47], v[44:45]
	v_cvt_pk_bf16_f32 v44, v52, v53
	v_cvt_pk_bf16_f32 v45, v54, v55
	v_cvt_pk_bf16_f32 v46, v124, v125
	v_cvt_pk_bf16_f32 v47, v126, v127
	global_store_dwordx4 v[152:153], v[44:47], off offset:256
	s_nop 1
	v_lshl_add_u64 v[44:45], s[8:9], 0, v[188:189]
	v_lshl_add_u64 v[128:129], v[44:45], 0, v[150:151]
	s_waitcnt vmcnt(7)
	v_lshlrev_b32_e32 v44, 16, v162
	v_and_b32_e32 v45, 0xffff0000, v162
	v_pk_add_f32 v[44:45], v[48:49], v[44:45]
	v_lshlrev_b32_e32 v48, 16, v164
	v_and_b32_e32 v49, 0xffff0000, v164
	v_lshlrev_b32_e32 v46, 16, v163
	v_and_b32_e32 v47, 0xffff0000, v163
	v_pk_add_f32 v[40:41], v[40:41], v[48:49]
	v_lshlrev_b32_e32 v48, 16, v165
	v_and_b32_e32 v49, 0xffff0000, v165
	v_pk_add_f32 v[46:47], v[50:51], v[46:47]
	v_pk_add_f32 v[42:43], v[42:43], v[48:49]
	v_cvt_pk_bf16_f32 v48, v44, v45
	v_cvt_pk_bf16_f32 v49, v46, v47
	v_cvt_pk_bf16_f32 v50, v40, v41
	v_cvt_pk_bf16_f32 v51, v42, v43
	global_store_dwordx4 v[128:129], v[48:51], off
	s_waitcnt vmcnt(7)
	s_nop 0
	v_lshlrev_b32_e32 v48, 16, v166
	v_and_b32_e32 v49, 0xffff0000, v166
	v_pk_add_f32 v[36:37], v[36:37], v[48:49]
	v_lshlrev_b32_e32 v48, 16, v167
	v_and_b32_e32 v49, 0xffff0000, v167
	v_pk_add_f32 v[38:39], v[38:39], v[48:49]
	v_lshlrev_b32_e32 v48, 16, v168
	v_and_b32_e32 v49, 0xffff0000, v168
	v_pk_add_f32 v[48:49], v[28:29], v[48:49]
	v_lshlrev_b32_e32 v28, 16, v169
	v_and_b32_e32 v29, 0xffff0000, v169
	v_pk_add_f32 v[50:51], v[30:31], v[28:29]
	v_cvt_pk_bf16_f32 v28, v36, v37
	v_cvt_pk_bf16_f32 v29, v38, v39
	v_cvt_pk_bf16_f32 v30, v48, v49
	v_cvt_pk_bf16_f32 v31, v50, v51
	global_store_dwordx4 v[128:129], v[28:31], off offset:256
	s_nop 1
	v_lshl_add_u64 v[28:29], s[8:9], 0, v[190:191]
	v_lshl_add_u64 v[128:129], v[28:29], 0, v[150:151]
	s_waitcnt vmcnt(7)
	v_lshlrev_b32_e32 v28, 16, v170
	v_and_b32_e32 v29, 0xffff0000, v170
	v_pk_add_f32 v[28:29], v[32:33], v[28:29]
	v_lshlrev_b32_e32 v32, 16, v172
	v_and_b32_e32 v33, 0xffff0000, v172
	v_lshlrev_b32_e32 v30, 16, v171
	v_and_b32_e32 v31, 0xffff0000, v171
	v_pk_add_f32 v[24:25], v[24:25], v[32:33]
	v_lshlrev_b32_e32 v32, 16, v173
	v_and_b32_e32 v33, 0xffff0000, v173
	v_pk_add_f32 v[30:31], v[34:35], v[30:31]
	v_pk_add_f32 v[26:27], v[26:27], v[32:33]
	v_cvt_pk_bf16_f32 v32, v28, v29
	v_cvt_pk_bf16_f32 v33, v30, v31
	v_cvt_pk_bf16_f32 v34, v24, v25
	v_cvt_pk_bf16_f32 v35, v26, v27
	global_store_dwordx4 v[128:129], v[32:35], off
	s_waitcnt vmcnt(7)
	s_nop 0
	v_lshlrev_b32_e32 v32, 16, v174
	v_and_b32_e32 v33, 0xffff0000, v174
	v_pk_add_f32 v[20:21], v[20:21], v[32:33]
	v_lshlrev_b32_e32 v32, 16, v175
	v_and_b32_e32 v33, 0xffff0000, v175
	v_pk_add_f32 v[22:23], v[22:23], v[32:33]
	v_lshlrev_b32_e32 v32, 16, v176
	v_and_b32_e32 v33, 0xffff0000, v176
	v_pk_add_f32 v[32:33], v[12:13], v[32:33]
	v_lshlrev_b32_e32 v12, 16, v177
	v_and_b32_e32 v13, 0xffff0000, v177
	v_pk_add_f32 v[34:35], v[14:15], v[12:13]
	v_cvt_pk_bf16_f32 v12, v20, v21
	v_cvt_pk_bf16_f32 v13, v22, v23
	v_cvt_pk_bf16_f32 v14, v32, v33
	v_cvt_pk_bf16_f32 v15, v34, v35
	global_store_dwordx4 v[128:129], v[12:15], off offset:256
	s_nop 1
	v_lshl_add_u64 v[12:13], s[8:9], 0, v[196:197]
	v_lshl_add_u64 v[128:129], v[12:13], 0, v[150:151]
	s_waitcnt vmcnt(7)
	v_lshlrev_b32_e32 v12, 16, v178
	v_and_b32_e32 v13, 0xffff0000, v178
	v_pk_add_f32 v[12:13], v[16:17], v[12:13]
	v_lshlrev_b32_e32 v16, 16, v180
	v_and_b32_e32 v17, 0xffff0000, v180
	v_lshlrev_b32_e32 v14, 16, v179
	v_and_b32_e32 v15, 0xffff0000, v179
	v_pk_add_f32 v[8:9], v[8:9], v[16:17]
	v_lshlrev_b32_e32 v16, 16, v181
	v_and_b32_e32 v17, 0xffff0000, v181
	v_pk_add_f32 v[14:15], v[18:19], v[14:15]
	v_pk_add_f32 v[10:11], v[10:11], v[16:17]
	v_cvt_pk_bf16_f32 v16, v12, v13
	v_cvt_pk_bf16_f32 v17, v14, v15
	v_cvt_pk_bf16_f32 v18, v8, v9
	v_cvt_pk_bf16_f32 v19, v10, v11
	global_store_dwordx4 v[128:129], v[16:19], off
	s_waitcnt vmcnt(7)
	s_nop 0
	v_lshlrev_b32_e32 v16, 16, v64
	v_and_b32_e32 v17, 0xffff0000, v64
	v_pk_add_f32 v[4:5], v[4:5], v[16:17]
	v_lshlrev_b32_e32 v16, 16, v65
	v_and_b32_e32 v17, 0xffff0000, v65
	v_pk_add_f32 v[6:7], v[6:7], v[16:17]
	v_lshlrev_b32_e32 v16, 16, v66
	v_and_b32_e32 v17, 0xffff0000, v66
	v_pk_add_f32 v[0:1], v[0:1], v[16:17]
	v_lshlrev_b32_e32 v16, 16, v67
	v_and_b32_e32 v17, 0xffff0000, v67
	v_pk_add_f32 v[2:3], v[2:3], v[16:17]
	v_cvt_pk_bf16_f32 v16, v4, v5
	v_cvt_pk_bf16_f32 v17, v6, v7
	v_cvt_pk_bf16_f32 v18, v0, v1
	v_cvt_pk_bf16_f32 v19, v2, v3
	global_store_dwordx4 v[128:129], v[16:19], off offset:256
	ds_bpermute_b32 v16, v157, v160
	s_lshl_b32 s0, s14, 2
	s_ashr_i32 s1, s0, 31
	s_lshl_b64 s[0:1], s[0:1], 2
	s_add_u32 s14, s50, s0
	s_waitcnt lgkmcnt(0)
	v_add_f32_e32 v16, v160, v16
	ds_bpermute_b32 v17, v158, v16
	s_addc_u32 s15, s51, s1
	s_and_saveexec_b64 s[0:1], s[4:5]
	s_cbranch_execz .LBB0_1304
	s_waitcnt lgkmcnt(0)
	v_add_f32_e32 v18, v16, v17
	v_lshlrev_b64 v[16:17], 7, v[148:149]
	v_lshl_add_u64 v[16:17], s[14:15], 0, v[16:17]
	global_store_dword v[16:17], v18, off

; #define GAS __attribute__((address_space(1)))
; #define PG8_STAGE(bufoff, gbase, voff) do { _Pragma("unroll") for (int _i = 0; _i < 2; ++_i) \
;         __builtin_amdgcn_global_load_lds((const unsigned*)((const char*)(gbase) + (voff)[_i]), (LAS unsigned*)(lds + (bufoff) + ldsw + _i * 8192), 16, 0, 0); } while (0)
; #define PG8_WAIT_V(n) asm volatile("s_waitcnt vmcnt(" #n ")" ::: "memory")
; #define PG8_BAR __builtin_amdgcn_s_barrier()
; template <class Epi, class Sched>
; DI void gemm_phase(LAS unsigned char* lds, const int wv, const int lda, const int ldb, const Sched& S, const Epi& E) {
;     ...
;     PG8_STAGE(PG8_SB(0, 0), cB, voffB); PG8_STAGE(PG8_SB(0, 1), cB + hstepB, voffB); PG8_STAGE(PG8_SA(0, 0), cA, voffA); PG8_STAGE(PG8_SA(0, 1), cA + hstepA, voffA);
;     if (wr == 1) PG8_BAR;
;     PG8_WAIT_V(2); PG8_BAR;
;     PG8_STAGE(PG8_SB(1, 0), cB + kstep, voffB); PG8_STAGE(PG8_SA(1, 0), cA + kstep, voffA); PG8_STAGE(PG8_SB(1, 1), cB + hstepB + kstep, voffB);
;     PG8_WAIT_V(6); PG8_BAR;
;     DI bool operator()(AccT& acc, const Unit& u, int wr, int wc, int fr, int fq) const {
;     ...
;             for (int m = 0; m < 4; ++m) { const bf16* rowp = xb + (size_t)(row0 + ai * HALF + m * 16) * XP + col0;
; #pragma unroll
;                 for (int bj = 0; bj < 2; ++bj) xv[m][bj] = *(const GAS u32x4*)(rowp + bj * HALF); }
.LBB0_1467:
	s_add_u32 s4, s10, 0x1fc28000
	v_and_b32_e32 v15, 15, v14
	v_bfe_u32 v14, v14, 4, 2
	s_addc_u32 s5, s11, 0
	v_lshlrev_b32_e32 v17, 4, v14
	s_cmp_eq_u32 s71, 3
	v_lshl_or_b32 v154, s1, 6, v15
	v_lshl_or_b32 v17, v15, 6, v17
	v_lshlrev_b32_e32 v15, 2, v15
	s_cselect_b32 s13, s5, s9
	s_cselect_b32 s12, s4, s8
	s_and_b32 s7, s0, 3
	s_lshl_b32 s0, s1, 13
	v_and_b32_e32 v18, 32, v15
	s_add_i32 m0, s31, 0x18000
	v_lshl_add_u64 v[6:7], v[6:7], 0, s[28:29]
	v_bitop3_b32 v19, v17, s0, v18 bitop3:0xde
	s_lshl_b32 s0, s7, 12
	s_waitcnt vmcnt(2)
	s_barrier
	global_load_lds_dwordx4 v[6:7], off
	v_lshl_add_u64 v[4:5], v[4:5], 0, s[28:29]
	s_add_i32 m0, s31, 0x1a000
	s_add_i32 s47, s31, 0x8000
	s_add_i32 s48, s31, 0xa000
	v_bitop3_b32 v155, v17, s0, v18 bitop3:0xde
	global_load_lds_dwordx4 v[4:5], off
	v_lshl_add_u64 v[0:1], v[0:1], 0, s[28:29]
	s_mov_b32 m0, s47
	s_add_u32 s0, s36, 0x200080
	global_load_lds_dwordx4 v[0:1], off
	v_lshl_add_u64 v[0:1], v[2:3], 0, s[28:29]
	s_mov_b32 m0, s48
	s_addc_u32 s1, s37, 0
	global_load_lds_dwordx4 v[0:1], off
	s_add_i32 m0, s31, 0x1c000
	v_lshl_add_u64 v[0:1], s[0:1], 0, v[184:185]
	global_load_lds_dwordx4 v[0:1], off
	v_lshl_add_u64 v[0:1], s[0:1], 0, v[136:137]
	s_add_i32 m0, s31, 0x1e000
	s_movk_i32 s0, 0x80
	global_load_lds_dwordx4 v[0:1], off
	v_lshlrev_b32_e32 v0, 6, v14
	v_bitop3_b32 v157, v0, 64, v15 bitop3:0x36
	v_bitop3_b32 v158, v0, s0, v15 bitop3:0x36
	v_lshlrev_b32_e32 v0, 17, v8
	v_and_b32_e32 v0, 0xfffc0000, v0
	v_lshl_add_u32 v0, v9, 14, v0
	v_and_b32_e32 v1, 1, v8
	s_cmpk_lt_u32 s6, 0x100
	v_lshl_or_b32 v0, v1, 6, v0
	s_cselect_b64 s[14:15], -1, 0
	s_ashr_i32 s50, s20, 31
	s_ashr_i32 s51, s17, 31
	s_lshl_b32 s0, s7, 2
	v_lshl_add_u32 v138, v10, 1, v0
	v_lshlrev_b32_e32 v0, 17, v11
	s_add_u32 s0, s10, s0
	v_and_b32_e32 v0, 0xfffc0000, v0
	s_waitcnt vmcnt(6)
	s_addc_u32 s1, s11, 0
	v_lshl_add_u32 v0, v12, 14, v0
	v_and_b32_e32 v1, 1, v11
	v_lshlrev_b32_e32 v16, 3, v14
	s_add_u32 s52, s0, 0x49c28000
	v_lshl_or_b32 v0, v1, 6, v0
	v_lshl_or_b32 v156, s7, 5, v16
	s_mov_b32 s49, 0
	v_cmp_eq_u32_e64 s[4:5], 0, v14
	s_addc_u32 s53, s1, 0
	v_mov_b32_e32 v139, v185
	v_lshl_add_u32 v140, v13, 1, v0
	v_mov_b32_e32 v141, v185
	v_add_u32_e32 v159, 0, v19
	s_barrier
	v_mbcnt_lo_u32_b32 v248, -1, 0
	v_mbcnt_hi_u32_b32 v248, -1, v248
	s_lshl_b32 s98, s90, 10
	s_add_i32 s98, s98, 0x22000
	v_lshl_add_u32 v246, v248, 4, s98
	v_and_b32_e32 v249, 15, v248
	v_lshrrev_b32_e32 v242, 4, v248
	v_lshrrev_b32_e32 v243, 2, v249
	v_lshl_add_u32 v242, v243, 4, v242
	v_and_b32_e32 v243, 3, v249
	v_lshl_add_u32 v242, v243, 2, v242
	v_lshl_add_u32 v247, v242, 4, s98
	v_lshrrev_b32_e32 v242, 4, v248
	v_bfe_u32 v243, v248, 2, 2
	v_lshl_add_u32 v243, v242, 2, v243
	v_sub_u32_e32 v243, v243, v249
	v_and_b32_e32 v249, 3, v248
	v_sub_u32_e32 v249, v249, v242
	v_lshlrev_b32_e32 v249, 4, v249
	s_movk_i32 s98, 0x1000
	v_mad_i32_i24 v240, v243, s98, v249
	v_ashrrev_i32_e32 v241, 31, v240
	s_branch .LBB0_1470

; #define GAS __attribute__((address_space(1)))
; DI unsigned pk2(float lo, float hi) { f32x2 v = {lo, hi}; bf16x2_t r = __builtin_convertvector(v, bf16x2_t); return __builtin_bit_cast(unsigned, r); }
;     DI bool operator()(AccT& acc, const Unit& u, int wr, int wc, int fr, int fq) const {
;     ...
;             for (int m = 0; m < 4; ++m) { const bf16* rowp = xb + (size_t)(row0 + ai * HALF + m * 16) * XP + col0;
; #pragma unroll
;                 for (int bj = 0; bj < 2; ++bj) xv[m][bj] = *(const GAS u32x4*)(rowp + bj * HALF); }
;             __builtin_amdgcn_sched_barrier(0);
; #pragma unroll
;             for (int m = 0; m < 4; ++m) { bf16* rowp = xo + (size_t)(row0 + ai * HALF + m * 16) * XP + col0; float s = 0.f;
; #pragma unroll
;                 for (int bj = 0; bj < 2; ++bj) { const u32x4 x = xv[m][bj]; const f32x4 a0 = acc[ai][bj][m][0], a1 = acc[ai][bj][m][1];
;                     const float y0 = bflo(x.x) + a0[0], y1 = bfhi(x.x) + a0[1], y2 = bflo(x.y) + a0[2], y3 = bfhi(x.y) + a0[3], y4 = bflo(x.z) + a1[0], y5 = bfhi(x.z) + a1[1], y6 = bflo(x.w) + a1[2], y7 = bfhi(x.w) + a1[3];
;                     s += (y0 * y0 + y1 * y1) + (y2 * y2 + y3 * y3) + (y4 * y4 + y5 * y5) + (y6 * y6 + y7 * y7);
;                     u32x4 w; w.x = pk2(y0, y1); w.y = pk2(y2, y3); w.z = pk2(y4, y5); w.w = pk2(y6, y7);
;                     *(GAS u32x4*)(rowp + bj * HALF) = w; }
.LBB0_1480:
	v_lshl_or_b32 v128, s18, 8, v156
	v_lshl_add_u32 v148, s30, 8, v154
	v_ashrrev_i32_e32 v129, 31, v128
	v_lshlrev_b64 v[150:151], 1, v[128:129]
	v_ashrrev_i32_e32 v149, 31, v148
	v_or_b32_e32 v146, 16, v148
	v_lshl_add_u64 v[152:153], s[8:9], 0, v[150:151]
	v_lshlrev_b64 v[196:197], 12, v[148:149]
	v_ashrrev_i32_e32 v147, 31, v146
	v_or_b32_e32 v144, 32, v148
	v_lshl_add_u64 v[128:129], v[152:153], 0, v[196:197]
	v_lshlrev_b64 v[198:199], 12, v[146:147]
	v_ashrrev_i32_e32 v145, 31, v144
	v_or_b32_e32 v142, 48, v148
	v_lshl_add_u64 v[242:243], v[128:129], 0, v[240:241]
	global_load_dwordx4 v[160:163], v[242:243], off
	v_lshl_add_u64 v[244:245], v[128:129], 0, v[240:241]
	global_load_dwordx4 v[164:167], v[244:245], off offset:256
	v_lshl_add_u64 v[128:129], v[152:153], 0, v[198:199]
	v_lshlrev_b64 v[200:201], 12, v[144:145]
	v_ashrrev_i32_e32 v143, 31, v142
	v_lshl_add_u64 v[242:243], v[128:129], 0, v[240:241]
	global_load_dwordx4 v[168:171], v[242:243], off
	v_lshl_add_u64 v[244:245], v[128:129], 0, v[240:241]
	global_load_dwordx4 v[172:175], v[244:245], off offset:256
	v_lshl_add_u64 v[128:129], v[152:153], 0, v[200:201]
	v_lshlrev_b64 v[202:203], 12, v[142:143]
	v_lshl_add_u64 v[242:243], v[128:129], 0, v[240:241]
	global_load_dwordx4 v[176:179], v[242:243], off
	v_lshl_add_u64 v[244:245], v[128:129], 0, v[240:241]
	global_load_dwordx4 v[180:183], v[244:245], off offset:256
	v_lshl_add_u64 v[128:129], v[152:153], 0, v[202:203]
	v_lshl_add_u64 v[242:243], v[128:129], 0, v[240:241]
	global_load_dwordx4 v[188:191], v[242:243], off
	s_nop 0
	v_lshl_add_u64 v[244:245], v[128:129], 0, v[240:241]
	global_load_dwordx4 v[128:131], v[244:245], off offset:256
	s_waitcnt vmcnt(0)
	ds_write_b128 v246, v[160:163]
	ds_read_b128 v[160:163], v247
	ds_write_b128 v246, v[164:167]
	ds_read_b128 v[164:167], v247
	ds_write_b128 v246, v[168:171]
	ds_read_b128 v[168:171], v247
	ds_write_b128 v246, v[172:175]
	ds_read_b128 v[172:175], v247
	ds_write_b128 v246, v[176:179]
	ds_read_b128 v[176:179], v247
	ds_write_b128 v246, v[180:183]
	ds_read_b128 v[180:183], v247
	s_waitcnt lgkmcnt(0)
	ds_write_b128 v246, v[188:191]
	ds_read_b128 v[188:191], v247
	ds_write_b128 v246, v[128:131]
	ds_read_b128 v[128:131], v247
	s_waitcnt lgkmcnt(0)
	v_lshlrev_b32_e32 v204, 16, v160
	v_and_b32_e32 v205, 0xffff0000, v160
	v_lshlrev_b32_e32 v160, 16, v161
	v_and_b32_e32 v161, 0xffff0000, v161
	v_pk_add_f32 v[126:127], v[126:127], v[160:161]
	v_lshlrev_b32_e32 v160, 16, v162
	v_and_b32_e32 v161, 0xffff0000, v162
	v_pk_add_f32 v[160:161], v[120:121], v[160:161]
	v_lshlrev_b32_e32 v120, 16, v163
	v_and_b32_e32 v121, 0xffff0000, v163
	v_lshl_add_u64 v[196:197], s[12:13], 0, v[196:197]
	v_pk_add_f32 v[124:125], v[124:125], v[204:205]
	v_pk_add_f32 v[162:163], v[122:123], v[120:121]
	v_lshl_add_u64 v[196:197], v[196:197], 0, v[150:151]
	v_cvt_pk_bf16_f32 v120, v124, v125
	v_cvt_pk_bf16_f32 v121, v126, v127
	v_cvt_pk_bf16_f32 v122, v160, v161
	v_cvt_pk_bf16_f32 v123, v162, v163
	global_store_dwordx4 v[196:197], v[120:123], off
	v_pk_mul_f32 v[204:205], v[124:125], v[124:125]
	v_pk_mul_f32 v[206:207], v[126:127], v[126:127]
	v_lshlrev_b32_e32 v120, 16, v164
	v_and_b32_e32 v121, 0xffff0000, v164
	v_pk_add_f32 v[116:117], v[116:117], v[120:121]
	v_lshlrev_b32_e32 v120, 16, v165
	v_and_b32_e32 v121, 0xffff0000, v165
	v_pk_add_f32 v[118:119], v[118:119], v[120:121]
	v_lshlrev_b32_e32 v120, 16, v166
	v_and_b32_e32 v121, 0xffff0000, v166
	v_pk_add_f32 v[120:121], v[112:113], v[120:121]
	v_lshlrev_b32_e32 v112, 16, v167
	v_and_b32_e32 v113, 0xffff0000, v167
	v_pk_add_f32 v[122:123], v[114:115], v[112:113]
	v_pk_mul_f32 v[112:113], v[116:117], v[116:117]
	v_pk_mul_f32 v[114:115], v[118:119], v[118:119]
	v_add_f32_e32 v112, v112, v113
	v_add_f32_e32 v114, v114, v115
	v_pk_mul_f32 v[208:209], v[160:161], v[160:161]
	v_pk_mul_f32 v[124:125], v[120:121], v[120:121]
	v_add_f32_e32 v112, v112, v114
	v_add_f32_e32 v114, v206, v207
	v_add_f32_e32 v115, v204, v205
	v_pk_mul_f32 v[210:211], v[162:163], v[162:163]
	v_pk_mul_f32 v[126:127], v[122:123], v[122:123]
	v_add_f32_e32 v113, v124, v125
	v_add_f32_e32 v114, v115, v114
	v_add_f32_e32 v115, v208, v209
	v_add_f32_e32 v126, v126, v127
	v_add_f32_e32 v112, v113, v112
	v_add_f32_e32 v113, v210, v211
	v_add_f32_e32 v114, v115, v114
	v_add_f32_e32 v112, v126, v112
	v_add_f32_e32 v113, v113, v114
	v_add_f32_e32 v160, v113, v112
	v_cvt_pk_bf16_f32 v112, v116, v117
	v_cvt_pk_bf16_f32 v113, v118, v119
	v_cvt_pk_bf16_f32 v114, v120, v121
	v_cvt_pk_bf16_f32 v115, v122, v123
	global_store_dwordx4 v[196:197], v[112:115], off offset:256
	s_nop 1
	v_lshl_add_u64 v[112:113], s[12:13], 0, v[198:199]
	v_lshl_add_u64 v[116:117], v[112:113], 0, v[150:151]
	v_lshlrev_b32_e32 v112, 16, v168
	v_and_b32_e32 v113, 0xffff0000, v168
	v_pk_add_f32 v[108:109], v[108:109], v[112:113]
	v_lshlrev_b32_e32 v112, 16, v169
	v_and_b32_e32 v113, 0xffff0000, v169
	v_pk_add_f32 v[110:111], v[110:111], v[112:113]
	v_lshlrev_b32_e32 v112, 16, v170
	v_and_b32_e32 v113, 0xffff0000, v170
	v_pk_add_f32 v[104:105], v[104:105], v[112:113]
	v_lshlrev_b32_e32 v112, 16, v171
	v_and_b32_e32 v113, 0xffff0000, v171
	v_pk_add_f32 v[106:107], v[106:107], v[112:113]
	v_cvt_pk_bf16_f32 v112, v108, v109
	v_cvt_pk_bf16_f32 v113, v110, v111
	v_cvt_pk_bf16_f32 v114, v104, v105
	v_cvt_pk_bf16_f32 v115, v106, v107
	global_store_dwordx4 v[116:117], v[112:115], off
	s_nop 1
	v_lshlrev_b32_e32 v112, 16, v172
	v_and_b32_e32 v113, 0xffff0000, v172
	v_pk_add_f32 v[100:101], v[100:101], v[112:113]
	v_lshlrev_b32_e32 v112, 16, v173
	v_and_b32_e32 v113, 0xffff0000, v173
	v_pk_add_f32 v[102:103], v[102:103], v[112:113]
; #define GAS __attribute__((address_space(1)))
; DI unsigned pk2(float lo, float hi) { f32x2 v = {lo, hi}; bf16x2_t r = __builtin_convertvector(v, bf16x2_t); return __builtin_bit_cast(unsigned, r); }
;     DI bool operator()(AccT& acc, const Unit& u, int wr, int wc, int fr, int fq) const {
;     ...
;             for (int m = 0; m < 4; ++m) { const bf16* rowp = xb + (size_t)(row0 + ai * HALF + m * 16) * XP + col0;
; #pragma unroll
;                 for (int bj = 0; bj < 2; ++bj) xv[m][bj] = *(const GAS u32x4*)(rowp + bj * HALF); }
;             __builtin_amdgcn_sched_barrier(0);
; #pragma unroll
;             for (int m = 0; m < 4; ++m) { bf16* rowp = xo + (size_t)(row0 + ai * HALF + m * 16) * XP + col0; float s = 0.f;
; #pragma unroll
;                 for (int bj = 0; bj < 2; ++bj) { const u32x4 x = xv[m][bj]; const f32x4 a0 = acc[ai][bj][m][0], a1 = acc[ai][bj][m][1];
;                     const float y0 = bflo(x.x) + a0[0], y1 = bfhi(x.x) + a0[1], y2 = bflo(x.y) + a0[2], y3 = bfhi(x.y) + a0[3], y4 = bflo(x.z) + a1[0], y5 = bfhi(x.z) + a1[1], y6 = bflo(x.w) + a1[2], y7 = bfhi(x.w) + a1[3];
;                     s += (y0 * y0 + y1 * y1) + (y2 * y2 + y3 * y3) + (y4 * y4 + y5 * y5) + (y6 * y6 + y7 * y7);
;                     u32x4 w; w.x = pk2(y0, y1); w.y = pk2(y2, y3); w.z = pk2(y4, y5); w.w = pk2(y6, y7);
;                     *(GAS u32x4*)(rowp + bj * HALF) = w; }
	v_lshlrev_b32_e32 v112, 16, v174
	v_and_b32_e32 v113, 0xffff0000, v174
	v_pk_add_f32 v[112:113], v[92:93], v[112:113]
	v_lshlrev_b32_e32 v92, 16, v175
	v_and_b32_e32 v93, 0xffff0000, v175
	v_pk_add_f32 v[114:115], v[94:95], v[92:93]
	v_cvt_pk_bf16_f32 v92, v100, v101
	v_cvt_pk_bf16_f32 v93, v102, v103
	v_cvt_pk_bf16_f32 v94, v112, v113
	v_cvt_pk_bf16_f32 v95, v114, v115
	global_store_dwordx4 v[116:117], v[92:95], off offset:256
	s_nop 1
	v_lshl_add_u64 v[92:93], s[12:13], 0, v[200:201]
	v_lshl_add_u64 v[116:117], v[92:93], 0, v[150:151]
	v_lshlrev_b32_e32 v92, 16, v176
	v_and_b32_e32 v93, 0xffff0000, v176
	v_pk_add_f32 v[92:93], v[96:97], v[92:93]
	v_lshlrev_b32_e32 v96, 16, v178
	v_and_b32_e32 v97, 0xffff0000, v178
	v_lshlrev_b32_e32 v94, 16, v177
	v_and_b32_e32 v95, 0xffff0000, v177
	v_pk_add_f32 v[88:89], v[88:89], v[96:97]
	v_lshlrev_b32_e32 v96, 16, v179
	v_and_b32_e32 v97, 0xffff0000, v179
	v_pk_add_f32 v[94:95], v[98:99], v[94:95]
	v_pk_add_f32 v[90:91], v[90:91], v[96:97]
	v_cvt_pk_bf16_f32 v96, v92, v93
	v_cvt_pk_bf16_f32 v97, v94, v95
	v_cvt_pk_bf16_f32 v98, v88, v89
	v_cvt_pk_bf16_f32 v99, v90, v91
	global_store_dwordx4 v[116:117], v[96:99], off
	s_nop 1
	v_lshlrev_b32_e32 v96, 16, v180
	v_and_b32_e32 v97, 0xffff0000, v180
	v_pk_add_f32 v[84:85], v[84:85], v[96:97]
	v_lshlrev_b32_e32 v96, 16, v181
	v_and_b32_e32 v97, 0xffff0000, v181
	v_pk_add_f32 v[86:87], v[86:87], v[96:97]
	v_lshlrev_b32_e32 v96, 16, v182
	v_and_b32_e32 v97, 0xffff0000, v182
	v_pk_add_f32 v[96:97], v[76:77], v[96:97]
	v_lshlrev_b32_e32 v76, 16, v183
	v_and_b32_e32 v77, 0xffff0000, v183
	v_pk_add_f32 v[98:99], v[78:79], v[76:77]
	v_cvt_pk_bf16_f32 v76, v84, v85
	v_cvt_pk_bf16_f32 v77, v86, v87
	v_cvt_pk_bf16_f32 v78, v96, v97
	v_cvt_pk_bf16_f32 v79, v98, v99
	global_store_dwordx4 v[116:117], v[76:79], off offset:256
	s_nop 1
	v_lshl_add_u64 v[76:77], s[12:13], 0, v[202:203]
	v_lshl_add_u64 v[124:125], v[76:77], 0, v[150:151]
	v_lshlrev_b32_e32 v76, 16, v188
	v_and_b32_e32 v77, 0xffff0000, v188
	v_pk_add_f32 v[76:77], v[80:81], v[76:77]
	v_lshlrev_b32_e32 v80, 16, v190
	v_and_b32_e32 v81, 0xffff0000, v190
	v_lshlrev_b32_e32 v78, 16, v189
	v_and_b32_e32 v79, 0xffff0000, v189
	v_pk_add_f32 v[80:81], v[72:73], v[80:81]
	v_lshlrev_b32_e32 v72, 16, v191
	v_and_b32_e32 v73, 0xffff0000, v191
	v_pk_add_f32 v[78:79], v[82:83], v[78:79]
	v_pk_add_f32 v[82:83], v[74:75], v[72:73]
	v_cvt_pk_bf16_f32 v72, v76, v77
	v_cvt_pk_bf16_f32 v73, v78, v79
	v_cvt_pk_bf16_f32 v74, v80, v81
	v_cvt_pk_bf16_f32 v75, v82, v83
	global_store_dwordx4 v[124:125], v[72:75], off
	s_nop 1
	v_lshlrev_b32_e32 v72, 16, v128
	v_and_b32_e32 v73, 0xffff0000, v128
	v_pk_add_f32 v[116:117], v[68:69], v[72:73]
	v_lshlrev_b32_e32 v68, 16, v129
	v_and_b32_e32 v69, 0xffff0000, v129
	v_pk_add_f32 v[118:119], v[70:71], v[68:69]
	v_lshlrev_b32_e32 v68, 16, v130
	v_and_b32_e32 v69, 0xffff0000, v130
	v_pk_add_f32 v[120:121], v[64:65], v[68:69]
	v_lshlrev_b32_e32 v64, 16, v131
	v_and_b32_e32 v65, 0xffff0000, v131
	v_pk_add_f32 v[122:123], v[66:67], v[64:65]
	v_cvt_pk_bf16_f32 v64, v116, v117
	v_cvt_pk_bf16_f32 v65, v118, v119
	v_cvt_pk_bf16_f32 v66, v120, v121
	v_cvt_pk_bf16_f32 v67, v122, v123
	global_store_dwordx4 v[124:125], v[64:67], off offset:256
	v_add_u32_e32 v74, 0x80, v148
	v_ashrrev_i32_e32 v75, 31, v74
	v_add_u32_e32 v72, 0x90, v148
	v_lshlrev_b64 v[182:183], 12, v[74:75]
	v_ashrrev_i32_e32 v73, 31, v72
	v_add_u32_e32 v70, 0xa0, v148
	v_lshl_add_u64 v[64:65], v[152:153], 0, v[182:183]
	v_lshlrev_b64 v[188:189], 12, v[72:73]
	v_ashrrev_i32_e32 v71, 31, v70
	v_add_u32_e32 v68, 0xb0, v148
	v_lshl_add_u64 v[242:243], v[64:65], 0, v[240:241]
	global_load_dwordx4 v[124:127], v[242:243], off
	v_lshl_add_u64 v[244:245], v[64:65], 0, v[240:241]
	global_load_dwordx4 v[128:131], v[244:245], off offset:256
	v_lshl_add_u64 v[64:65], v[152:153], 0, v[188:189]
	v_lshlrev_b64 v[190:191], 12, v[70:71]
	v_ashrrev_i32_e32 v69, 31, v68
	v_lshl_add_u64 v[242:243], v[64:65], 0, v[240:241]
	global_load_dwordx4 v[162:165], v[242:243], off
	v_lshl_add_u64 v[244:245], v[64:65], 0, v[240:241]
	global_load_dwordx4 v[166:169], v[244:245], off offset:256
	v_lshl_add_u64 v[64:65], v[152:153], 0, v[190:191]
	v_lshlrev_b64 v[196:197], 12, v[68:69]
	v_lshl_add_u64 v[242:243], v[64:65], 0, v[240:241]
	global_load_dwordx4 v[170:173], v[242:243], off
	v_lshl_add_u64 v[244:245], v[64:65], 0, v[240:241]
	global_load_dwordx4 v[174:177], v[244:245], off offset:256
	v_lshl_add_u64 v[64:65], v[152:153], 0, v[196:197]
	v_lshl_add_u64 v[242:243], v[64:65], 0, v[240:241]
	global_load_dwordx4 v[178:181], v[242:243], off
	s_nop 0
	v_lshl_add_u64 v[244:245], v[64:65], 0, v[240:241]
	global_load_dwordx4 v[64:67], v[244:245], off offset:256
	v_lshl_add_u64 v[152:153], s[12:13], 0, v[182:183]
	s_waitcnt vmcnt(0)
	ds_write_b128 v246, v[124:127]
	ds_read_b128 v[124:127], v247
	ds_write_b128 v246, v[128:131]
	ds_read_b128 v[128:131], v247
	ds_write_b128 v246, v[162:165]
	ds_read_b128 v[162:165], v247
	ds_write_b128 v246, v[166:169]
	ds_read_b128 v[166:169], v247
	ds_write_b128 v246, v[170:173]
	ds_read_b128 v[170:173], v247
	ds_write_b128 v246, v[174:177]
	ds_read_b128 v[174:177], v247
	s_waitcnt lgkmcnt(0)
	ds_write_b128 v246, v[178:181]
	ds_read_b128 v[178:181], v247
	ds_write_b128 v246, v[64:67]
	ds_read_b128 v[64:67], v247
	s_waitcnt lgkmcnt(0)
; #define GAS __attribute__((address_space(1)))
; DI unsigned pk2(float lo, float hi) { f32x2 v = {lo, hi}; bf16x2_t r = __builtin_convertvector(v, bf16x2_t); return __builtin_bit_cast(unsigned, r); }
;     DI bool operator()(AccT& acc, const Unit& u, int wr, int wc, int fr, int fq) const {
;     ...
;             for (int m = 0; m < 4; ++m) { bf16* rowp = xo + (size_t)(row0 + ai * HALF + m * 16) * XP + col0; float s = 0.f;
; #pragma unroll
;                 for (int bj = 0; bj < 2; ++bj) { const u32x4 x = xv[m][bj]; const f32x4 a0 = acc[ai][bj][m][0], a1 = acc[ai][bj][m][1];
;                     const float y0 = bflo(x.x) + a0[0], y1 = bfhi(x.x) + a0[1], y2 = bflo(x.y) + a0[2], y3 = bfhi(x.y) + a0[3], y4 = bflo(x.z) + a1[0], y5 = bfhi(x.z) + a1[1], y6 = bflo(x.w) + a1[2], y7 = bfhi(x.w) + a1[3];
;                     s += (y0 * y0 + y1 * y1) + (y2 * y2 + y3 * y3) + (y4 * y4 + y5 * y5) + (y6 * y6 + y7 * y7);
;                     u32x4 w; w.x = pk2(y0, y1); w.y = pk2(y2, y3); w.z = pk2(y4, y5); w.w = pk2(y6, y7);
;                     *(GAS u32x4*)(rowp + bj * HALF) = w; }
;                 ps[ai][m] = s; }
;             __builtin_amdgcn_sched_barrier(0);
;         }
;         { int a16 = ((fr + 16 * fq) ^ 16) << 2, a32 = ((fr + 16 * fq) ^ 32) << 2;
; #pragma unroll
;           for (int ai = 0; ai < 2; ++ai)
; #pragma unroll
;               for (int m = 0; m < 4; ++m) { float s = ps[ai][m];
;                   s += __builtin_bit_cast(float, __builtin_amdgcn_ds_bpermute(a16, __builtin_bit_cast(int, s)));
;                   s += __builtin_bit_cast(float, __builtin_amdgcn_ds_bpermute(a32, __builtin_bit_cast(int, s)));
;                   if (fq == 0) ssq[(size_t)(row0 + ai * HALF + m * 16) * 32 + u.pn * 4 + wc] = s; } }
	v_lshlrev_b32_e32 v182, 16, v124
	v_and_b32_e32 v183, 0xffff0000, v124
	v_lshlrev_b32_e32 v124, 16, v125
	v_and_b32_e32 v125, 0xffff0000, v125
	v_pk_add_f32 v[62:63], v[62:63], v[124:125]
	v_lshlrev_b32_e32 v124, 16, v126
	v_and_b32_e32 v125, 0xffff0000, v126
	v_pk_add_f32 v[56:57], v[56:57], v[124:125]
	v_lshlrev_b32_e32 v124, 16, v127
	v_and_b32_e32 v125, 0xffff0000, v127
	v_pk_add_f32 v[60:61], v[60:61], v[182:183]
	v_pk_add_f32 v[58:59], v[58:59], v[124:125]
	v_lshl_add_u64 v[152:153], v[152:153], 0, v[150:151]
	v_cvt_pk_bf16_f32 v124, v60, v61
	v_cvt_pk_bf16_f32 v125, v62, v63
	v_cvt_pk_bf16_f32 v126, v56, v57
	v_cvt_pk_bf16_f32 v127, v58, v59
	global_store_dwordx4 v[152:153], v[124:127], off
	s_waitcnt vmcnt(7)
	s_nop 0
	v_lshlrev_b32_e32 v124, 16, v128
	v_and_b32_e32 v125, 0xffff0000, v128
	v_pk_add_f32 v[52:53], v[52:53], v[124:125]
	v_lshlrev_b32_e32 v124, 16, v129
	v_and_b32_e32 v125, 0xffff0000, v129
	v_pk_add_f32 v[54:55], v[54:55], v[124:125]
	v_lshlrev_b32_e32 v124, 16, v130
	v_and_b32_e32 v125, 0xffff0000, v130
	v_pk_add_f32 v[124:125], v[44:45], v[124:125]
	v_lshlrev_b32_e32 v44, 16, v131
	v_and_b32_e32 v45, 0xffff0000, v131
	v_pk_add_f32 v[126:127], v[46:47], v[44:45]
	v_cvt_pk_bf16_f32 v44, v52, v53
	v_cvt_pk_bf16_f32 v45, v54, v55
	v_cvt_pk_bf16_f32 v46, v124, v125
	v_cvt_pk_bf16_f32 v47, v126, v127
	global_store_dwordx4 v[152:153], v[44:47], off offset:256
	s_nop 1
	v_lshl_add_u64 v[44:45], s[12:13], 0, v[188:189]
	v_lshl_add_u64 v[128:129], v[44:45], 0, v[150:151]
	s_waitcnt vmcnt(7)
	v_lshlrev_b32_e32 v44, 16, v162
	v_and_b32_e32 v45, 0xffff0000, v162
	v_pk_add_f32 v[44:45], v[48:49], v[44:45]
	v_lshlrev_b32_e32 v48, 16, v164
	v_and_b32_e32 v49, 0xffff0000, v164
	v_lshlrev_b32_e32 v46, 16, v163
	v_and_b32_e32 v47, 0xffff0000, v163
	v_pk_add_f32 v[40:41], v[40:41], v[48:49]
	v_lshlrev_b32_e32 v48, 16, v165
	v_and_b32_e32 v49, 0xffff0000, v165
	v_pk_add_f32 v[46:47], v[50:51], v[46:47]
	v_pk_add_f32 v[42:43], v[42:43], v[48:49]
	v_cvt_pk_bf16_f32 v48, v44, v45
	v_cvt_pk_bf16_f32 v49, v46, v47
	v_cvt_pk_bf16_f32 v50, v40, v41
	v_cvt_pk_bf16_f32 v51, v42, v43
	global_store_dwordx4 v[128:129], v[48:51], off
	s_waitcnt vmcnt(7)
	s_nop 0
	v_lshlrev_b32_e32 v48, 16, v166
	v_and_b32_e32 v49, 0xffff0000, v166
	v_pk_add_f32 v[36:37], v[36:37], v[48:49]
	v_lshlrev_b32_e32 v48, 16, v167
	v_and_b32_e32 v49, 0xffff0000, v167
	v_pk_add_f32 v[38:39], v[38:39], v[48:49]
	v_lshlrev_b32_e32 v48, 16, v168
	v_and_b32_e32 v49, 0xffff0000, v168
	v_pk_add_f32 v[48:49], v[28:29], v[48:49]
	v_lshlrev_b32_e32 v28, 16, v169
	v_and_b32_e32 v29, 0xffff0000, v169
	v_pk_add_f32 v[50:51], v[30:31], v[28:29]
	v_cvt_pk_bf16_f32 v28, v36, v37
	v_cvt_pk_bf16_f32 v29, v38, v39
	v_cvt_pk_bf16_f32 v30, v48, v49
	v_cvt_pk_bf16_f32 v31, v50, v51
	global_store_dwordx4 v[128:129], v[28:31], off offset:256
	s_nop 1
	v_lshl_add_u64 v[28:29], s[12:13], 0, v[190:191]
	v_lshl_add_u64 v[128:129], v[28:29], 0, v[150:151]
	s_waitcnt vmcnt(7)
	v_lshlrev_b32_e32 v28, 16, v170
	v_and_b32_e32 v29, 0xffff0000, v170
	v_pk_add_f32 v[28:29], v[32:33], v[28:29]
	v_lshlrev_b32_e32 v32, 16, v172
	v_and_b32_e32 v33, 0xffff0000, v172
	v_lshlrev_b32_e32 v30, 16, v171
	v_and_b32_e32 v31, 0xffff0000, v171
	v_pk_add_f32 v[24:25], v[24:25], v[32:33]
	v_lshlrev_b32_e32 v32, 16, v173
	v_and_b32_e32 v33, 0xffff0000, v173
	v_pk_add_f32 v[30:31], v[34:35], v[30:31]
	v_pk_add_f32 v[26:27], v[26:27], v[32:33]
	v_cvt_pk_bf16_f32 v32, v28, v29
	v_cvt_pk_bf16_f32 v33, v30, v31
	v_cvt_pk_bf16_f32 v34, v24, v25
	v_cvt_pk_bf16_f32 v35, v26, v27
	global_store_dwordx4 v[128:129], v[32:35], off
	s_waitcnt vmcnt(7)
	s_nop 0
	v_lshlrev_b32_e32 v32, 16, v174
	v_and_b32_e32 v33, 0xffff0000, v174
	v_pk_add_f32 v[20:21], v[20:21], v[32:33]
	v_lshlrev_b32_e32 v32, 16, v175
	v_and_b32_e32 v33, 0xffff0000, v175
	v_pk_add_f32 v[22:23], v[22:23], v[32:33]
	v_lshlrev_b32_e32 v32, 16, v176
	v_and_b32_e32 v33, 0xffff0000, v176
	v_pk_add_f32 v[32:33], v[12:13], v[32:33]
	v_lshlrev_b32_e32 v12, 16, v177
	v_and_b32_e32 v13, 0xffff0000, v177
	v_pk_add_f32 v[34:35], v[14:15], v[12:13]
	v_cvt_pk_bf16_f32 v12, v20, v21
	v_cvt_pk_bf16_f32 v13, v22, v23
	v_cvt_pk_bf16_f32 v14, v32, v33
	v_cvt_pk_bf16_f32 v15, v34, v35
	global_store_dwordx4 v[128:129], v[12:15], off offset:256
	s_nop 1
	v_lshl_add_u64 v[12:13], s[12:13], 0, v[196:197]
	v_lshl_add_u64 v[128:129], v[12:13], 0, v[150:151]
	s_waitcnt vmcnt(7)
	v_lshlrev_b32_e32 v12, 16, v178
	v_and_b32_e32 v13, 0xffff0000, v178
	v_pk_add_f32 v[12:13], v[16:17], v[12:13]
	v_lshlrev_b32_e32 v16, 16, v180
	v_and_b32_e32 v17, 0xffff0000, v180
	v_lshlrev_b32_e32 v14, 16, v179
	v_and_b32_e32 v15, 0xffff0000, v179
	v_pk_add_f32 v[8:9], v[8:9], v[16:17]
	v_lshlrev_b32_e32 v16, 16, v181
	v_and_b32_e32 v17, 0xffff0000, v181
	v_pk_add_f32 v[14:15], v[18:19], v[14:15]
	v_pk_add_f32 v[10:11], v[10:11], v[16:17]
	v_cvt_pk_bf16_f32 v16, v12, v13
	v_cvt_pk_bf16_f32 v17, v14, v15
	v_cvt_pk_bf16_f32 v18, v8, v9
	v_cvt_pk_bf16_f32 v19, v10, v11
	global_store_dwordx4 v[128:129], v[16:19], off
	s_waitcnt vmcnt(7)
	s_nop 0
	v_lshlrev_b32_e32 v16, 16, v64
	v_and_b32_e32 v17, 0xffff0000, v64
	v_pk_add_f32 v[4:5], v[4:5], v[16:17]
	v_lshlrev_b32_e32 v16, 16, v65
	v_and_b32_e32 v17, 0xffff0000, v65
	v_pk_add_f32 v[6:7], v[6:7], v[16:17]
	v_lshlrev_b32_e32 v16, 16, v66
	v_and_b32_e32 v17, 0xffff0000, v66
	v_pk_add_f32 v[0:1], v[0:1], v[16:17]
	v_lshlrev_b32_e32 v16, 16, v67
	v_and_b32_e32 v17, 0xffff0000, v67
	v_pk_add_f32 v[2:3], v[2:3], v[16:17]
	v_cvt_pk_bf16_f32 v16, v4, v5
	v_cvt_pk_bf16_f32 v17, v6, v7
	v_cvt_pk_bf16_f32 v18, v0, v1
	v_cvt_pk_bf16_f32 v19, v2, v3
	global_store_dwordx4 v[128:129], v[16:19], off offset:256
	ds_bpermute_b32 v16, v157, v160
	s_lshl_b32 s0, s18, 2
	s_ashr_i32 s1, s0, 31
	s_lshl_b64 s[0:1], s[0:1], 2
	s_add_u32 s18, s52, s0
	s_waitcnt lgkmcnt(0)
	v_add_f32_e32 v16, v160, v16
	ds_bpermute_b32 v17, v158, v16
	s_addc_u32 s19, s53, s1
	s_and_saveexec_b64 s[0:1], s[4:5]
	s_cbranch_execz .LBB0_1482
	s_waitcnt lgkmcnt(0)
	v_add_f32_e32 v18, v16, v17
	v_lshlrev_b64 v[16:17], 7, v[148:149]
	v_lshl_add_u64 v[16:17], s[18:19], 0, v[16:17]
	global_store_dword v[16:17], v18, off
